# G3 pass 2: r fragments of rounds 1-15 loaded once right after round 0's load into spare VGPR quads; per-round load + vmcnt(0) drain (store ack + load latency x15) removed
# speedup vs baseline: 1.0053x; 1.0017x over previous
.LBB0_1377:
	s_or_b64 exec, exec, s[6:7]
	s_ashr_i32 s0, s24, 2
	s_ashr_i32 s1, s0, 31
	s_lshl_b64 s[0:1], s[0:1], 6
	s_lshl_b32 s6, s23, 5
	s_or_b32 s0, s0, s6
	v_lshlrev_b32_e32 v12, 4, v205
	v_or_b32_e32 v22, s0, v204
	v_mov_b32_e32 v23, s1
	v_readlane_b32 s68, v251, 9
	v_lshlrev_b64 v[26:27], 11, v[22:23]
	v_lshl_or_b32 v28, s44, 1, v12
	v_lshlrev_b32_e32 v10, 5, v205
	v_readlane_b32 s76, v251, 17
	v_readlane_b32 s77, v251, 18
	v_or_b32_e32 v26, v26, v28
	s_nop 3
	global_load_dwordx4 v[2:5], v10, s[76:77] offset:16
	global_load_dwordx4 v[6:9], v10, s[76:77]
	s_waitcnt lgkmcnt(0)
	v_lshl_add_u64 v[10:11], s[60:61], 0, v[26:27]
	global_load_dwordx4 v[18:21], v[10:11], off
	v_or_b32_e32 v128, 2, v22
	v_mov_b32_e32 v129, v23
	v_lshlrev_b64 v[130:131], 11, v[128:129]
	v_or_b32_e32 v130, v130, v28
	v_lshl_add_u64 v[128:129], s[60:61], 0, v[130:131]
	global_load_dwordx4 v[64:67], v[128:129], off
	v_or_b32_e32 v128, 4, v22
	v_mov_b32_e32 v129, v23
	v_lshlrev_b64 v[130:131], 11, v[128:129]
	v_or_b32_e32 v130, v130, v28
	v_lshl_add_u64 v[128:129], s[60:61], 0, v[130:131]
	global_load_dwordx4 v[68:71], v[128:129], off
	v_or_b32_e32 v128, 6, v22
	v_mov_b32_e32 v129, v23
	v_lshlrev_b64 v[130:131], 11, v[128:129]
	v_or_b32_e32 v130, v130, v28
	v_lshl_add_u64 v[128:129], s[60:61], 0, v[130:131]
	global_load_dwordx4 v[72:75], v[128:129], off
	v_or_b32_e32 v128, 8, v22
	v_mov_b32_e32 v129, v23
	v_lshlrev_b64 v[130:131], 11, v[128:129]
	v_or_b32_e32 v130, v130, v28
	v_lshl_add_u64 v[128:129], s[60:61], 0, v[130:131]
	global_load_dwordx4 v[76:79], v[128:129], off
	v_or_b32_e32 v128, 10, v22
	v_mov_b32_e32 v129, v23
	v_lshlrev_b64 v[130:131], 11, v[128:129]
	v_or_b32_e32 v130, v130, v28
	v_lshl_add_u64 v[128:129], s[60:61], 0, v[130:131]
	global_load_dwordx4 v[80:83], v[128:129], off
	v_or_b32_e32 v128, 12, v22
	v_mov_b32_e32 v129, v23
	v_lshlrev_b64 v[130:131], 11, v[128:129]
	v_or_b32_e32 v130, v130, v28
	v_lshl_add_u64 v[128:129], s[60:61], 0, v[130:131]
	global_load_dwordx4 v[84:87], v[128:129], off
	v_or_b32_e32 v128, 14, v22
	v_mov_b32_e32 v129, v23
	v_lshlrev_b64 v[130:131], 11, v[128:129]
	v_or_b32_e32 v130, v130, v28
	v_lshl_add_u64 v[128:129], s[60:61], 0, v[130:131]
	global_load_dwordx4 v[88:91], v[128:129], off
	v_or_b32_e32 v128, 16, v22
	v_mov_b32_e32 v129, v23
	v_lshlrev_b64 v[130:131], 11, v[128:129]
	v_or_b32_e32 v130, v130, v28
	v_lshl_add_u64 v[128:129], s[60:61], 0, v[130:131]
	global_load_dwordx4 v[92:95], v[128:129], off
	v_or_b32_e32 v128, 18, v22
	v_mov_b32_e32 v129, v23
	v_lshlrev_b64 v[130:131], 11, v[128:129]
	v_or_b32_e32 v130, v130, v28
	v_lshl_add_u64 v[128:129], s[60:61], 0, v[130:131]
	global_load_dwordx4 v[96:99], v[128:129], off
	v_or_b32_e32 v128, 20, v22
	v_mov_b32_e32 v129, v23
	v_lshlrev_b64 v[130:131], 11, v[128:129]
	v_or_b32_e32 v130, v130, v28
	v_lshl_add_u64 v[128:129], s[60:61], 0, v[130:131]
	global_load_dwordx4 v[100:103], v[128:129], off
	v_or_b32_e32 v128, 22, v22
	v_mov_b32_e32 v129, v23
	v_lshlrev_b64 v[130:131], 11, v[128:129]
	v_or_b32_e32 v130, v130, v28
	v_lshl_add_u64 v[128:129], s[60:61], 0, v[130:131]
	global_load_dwordx4 v[104:107], v[128:129], off
	v_or_b32_e32 v128, 24, v22
	v_mov_b32_e32 v129, v23
	v_lshlrev_b64 v[130:131], 11, v[128:129]
	v_or_b32_e32 v130, v130, v28
	v_lshl_add_u64 v[128:129], s[60:61], 0, v[130:131]
	global_load_dwordx4 v[108:111], v[128:129], off
	v_or_b32_e32 v128, 26, v22
	v_mov_b32_e32 v129, v23
	v_lshlrev_b64 v[130:131], 11, v[128:129]
	v_or_b32_e32 v130, v130, v28
	v_lshl_add_u64 v[128:129], s[60:61], 0, v[130:131]
	global_load_dwordx4 v[112:115], v[128:129], off
	v_or_b32_e32 v128, 28, v22
	v_mov_b32_e32 v129, v23
	v_lshlrev_b64 v[130:131], 11, v[128:129]
	v_or_b32_e32 v130, v130, v28
	v_lshl_add_u64 v[128:129], s[60:61], 0, v[130:131]
	global_load_dwordx4 v[116:119], v[128:129], off
	v_or_b32_e32 v128, 30, v22
	v_mov_b32_e32 v129, v23
	v_lshlrev_b64 v[130:131], 11, v[128:129]
	v_or_b32_e32 v130, v130, v28
	v_lshl_add_u64 v[128:129], s[60:61], 0, v[130:131]
	global_load_dwordx4 v[120:123], v[128:129], off
	s_mov_b64 s[8:9], s[76:77]
	v_mul_u32_u24_e32 v10, 0x210, v204
	v_add3_u32 v29, s22, v12, v10
	ds_read_b128 v[14:17], v29
	v_lshl_add_u32 v10, v204, 2, s22
	v_add_u32_e32 v30, 0x4000, v10
	ds_read2_b32 v[24:25], v30 offset0:128 offset1:130
	ds_read_b128 v[10:13], v29 offset:1056
	v_readlane_b32 s69, v251, 10
	s_waitcnt lgkmcnt(2)
	v_lshlrev_b32_e32 v32, 16, v14
	v_and_b32_e32 v33, 0xffff0000, v14
	s_waitcnt lgkmcnt(1)
	v_pk_mul_f32 v[32:33], v[24:25], v[32:33] op_sel_hi:[0,1]
	v_lshlrev_b32_e32 v14, 16, v15
	v_and_b32_e32 v15, 0xffff0000, v15
	v_lshlrev_b32_e32 v34, 16, v16
	v_pk_mul_f32 v[14:15], v[24:25], v[14:15] op_sel_hi:[0,1]
	v_readlane_b32 s70, v251, 11
	v_readlane_b32 s71, v251, 12
	v_readlane_b32 s72, v251, 13
	v_readlane_b32 s73, v251, 14
	v_readlane_b32 s74, v251, 15
	v_readlane_b32 s75, v251, 16
	v_readlane_b32 s78, v251, 19
	v_readlane_b32 s79, v251, 20
	v_readlane_b32 s80, v251, 21
	v_readlane_b32 s81, v251, 22
	v_readlane_b32 s82, v251, 23
	v_readlane_b32 s83, v251, 24
	s_waitcnt vmcnt(1)
	v_pk_mul_f32 v[32:33], v[6:7], v[32:33]
	v_pk_mul_f32 v[14:15], v[8:9], v[14:15]
	s_waitcnt vmcnt(0)
	v_lshlrev_b32_e32 v31, 16, v18
	v_and_b32_e32 v35, 0xffff0000, v18
	v_lshlrev_b32_e32 v40, 16, v19
	v_and_b32_e32 v41, 0xffff0000, v19
	v_mul_f32_e32 v18, 0xbfb8aa3b, v31
	v_mul_f32_e32 v19, 0xbfb8aa3b, v35
	v_exp_f32_e32 v18, v18
	v_exp_f32_e32 v19, v19
	v_mul_f32_e32 v36, 0xbfb8aa3b, v40
	v_mul_f32_e32 v37, 0xbfb8aa3b, v41
	v_exp_f32_e32 v36, v36
	v_exp_f32_e32 v37, v37
	v_pk_add_f32 v[18:19], v[18:19], 1.0 op_sel_hi:[1,0]
	v_lshlrev_b32_e32 v42, 16, v20
	v_div_scale_f32 v43, s[0:1], v19, v19, v35
	v_pk_add_f32 v[36:37], v[36:37], 1.0 op_sel_hi:[1,0]
	v_div_scale_f32 v45, s[0:1], v18, v18, v31
	v_rcp_f32_e32 v51, v43
	v_div_scale_f32 v47, s[6:7], v37, v37, v41
	v_rcp_f32_e32 v52, v45
	v_div_scale_f32 v49, s[8:9], v36, v36, v40
	v_rcp_f32_e32 v53, v47
	v_rcp_f32_e32 v54, v49
	v_fma_f32 v55, -v43, v51, 1.0
	v_div_scale_f32 v44, vcc, v35, v19, v35
	v_fma_f32 v56, -v45, v52, 1.0
	v_fmac_f32_e32 v51, v55, v51
	v_div_scale_f32 v46, s[0:1], v31, v18, v31
	v_fma_f32 v57, -v47, v53, 1.0
	v_fmac_f32_e32 v52, v56, v52
	v_mul_f32_e32 v55, v44, v51
	v_and_b32_e32 v20, 0xffff0000, v20
	v_div_scale_f32 v48, s[6:7], v41, v37, v41
	v_fma_f32 v58, -v49, v54, 1.0
	v_fmac_f32_e32 v53, v57, v53
	v_mul_f32_e32 v56, v46, v52
	v_fma_f32 v59, -v43, v55, v44
	v_mul_f32_e32 v38, 0xbfb8aa3b, v42
	v_mul_f32_e32 v39, 0xbfb8aa3b, v20
	v_div_scale_f32 v50, s[8:9], v40, v36, v40
	v_fmac_f32_e32 v54, v58, v54
	v_mul_f32_e32 v57, v48, v53
	v_fma_f32 v60, -v45, v56, v46
	v_fmac_f32_e32 v55, v59, v51
	v_exp_f32_e32 v38, v38
	v_exp_f32_e32 v39, v39
	v_mul_f32_e32 v58, v50, v54
	v_fma_f32 v61, -v47, v57, v48
	v_fmac_f32_e32 v56, v60, v52
	v_fma_f32 v43, -v43, v55, v44
	v_fma_f32 v62, -v49, v58, v50
	v_fmac_f32_e32 v57, v61, v53
	v_fma_f32 v44, -v45, v56, v46
	v_div_fmas_f32 v43, v43, v51, v55
	s_mov_b64 vcc, s[0:1]
	v_fmac_f32_e32 v58, v62, v54
	v_fma_f32 v45, -v47, v57, v48
	v_div_fixup_f32 v19, v43, v19, v35
	v_div_fmas_f32 v35, v44, v52, v56
	s_mov_b64 vcc, s[6:7]
	v_fma_f32 v46, -v49, v58, v50
	v_div_fixup_f32 v18, v35, v18, v31
	v_div_fmas_f32 v31, v45, v53, v57
	s_mov_b64 vcc, s[8:9]
	v_pk_add_f32 v[38:39], v[38:39], 1.0 op_sel_hi:[1,0]
	v_pk_mul_f32 v[18:19], v[32:33], v[18:19]
	v_div_fixup_f32 v33, v31, v37, v41
	v_div_fmas_f32 v31, v46, v54, v58
	v_div_fixup_f32 v32, v31, v36, v40
	v_div_scale_f32 v31, s[0:1], v39, v39, v20
	v_rcp_f32_e32 v36, v31
	v_and_b32_e32 v35, 0xffff0000, v16
	v_pk_mul_f32 v[32:33], v[14:15], v[32:33]
	v_pk_mul_f32 v[14:15], v[24:25], v[34:35] op_sel_hi:[0,1]
	v_fma_f32 v16, -v31, v36, 1.0
	v_fmac_f32_e32 v36, v16, v36
	v_div_scale_f32 v16, vcc, v20, v39, v20
	v_mul_f32_e32 v34, v16, v36
	v_fma_f32 v35, -v31, v34, v16
	v_fmac_f32_e32 v34, v35, v36
	v_fma_f32 v16, -v31, v34, v16
	v_div_scale_f32 v31, s[0:1], v38, v38, v42
	v_rcp_f32_e32 v37, v31
	v_div_fmas_f32 v16, v16, v36, v34
	v_div_fixup_f32 v35, v16, v39, v20
	v_and_b32_e32 v36, 0xffff0000, v21
	v_fma_f32 v16, -v31, v37, 1.0
	v_fmac_f32_e32 v37, v16, v37
	v_div_scale_f32 v16, vcc, v42, v38, v42
	v_mul_f32_e32 v20, v16, v37
	v_fma_f32 v34, -v31, v20, v16
	v_fmac_f32_e32 v20, v34, v37
	v_fma_f32 v16, -v31, v20, v16
	v_lshlrev_b32_e32 v31, 16, v21
	v_div_fmas_f32 v16, v16, v37, v20
	v_mul_f32_e32 v20, 0xbfb8aa3b, v31
	v_mul_f32_e32 v21, 0xbfb8aa3b, v36
	v_exp_f32_e32 v20, v20
	v_exp_f32_e32 v21, v21
	v_div_fixup_f32 v34, v16, v38, v42
	v_pk_mul_f32 v[14:15], v[2:3], v[14:15]
	v_pk_add_f32 v[20:21], v[20:21], 1.0 op_sel_hi:[1,0]
	s_nop 0
	v_div_scale_f32 v16, s[0:1], v21, v21, v36
	v_rcp_f32_e32 v37, v16
	v_pk_mul_f32 v[34:35], v[14:15], v[34:35]
	v_lshlrev_b32_e32 v14, 16, v17
	v_and_b32_e32 v15, 0xffff0000, v17
	v_fma_f32 v17, -v16, v37, 1.0
	v_fmac_f32_e32 v37, v17, v37
	v_div_scale_f32 v17, vcc, v36, v21, v36
	v_pk_mul_f32 v[14:15], v[24:25], v[14:15] op_sel_hi:[0,1]
	v_mul_f32_e32 v24, v17, v37
	v_fma_f32 v38, -v16, v24, v17
	v_fmac_f32_e32 v24, v38, v37
	v_div_scale_f32 v38, s[0:1], v20, v20, v31
	v_rcp_f32_e32 v39, v38
	v_fma_f32 v16, -v16, v24, v17
	v_div_fmas_f32 v16, v16, v37, v24
	v_div_fixup_f32 v17, v16, v21, v36
	v_fma_f32 v16, -v38, v39, 1.0
	v_fmac_f32_e32 v39, v16, v39
	v_div_scale_f32 v16, vcc, v31, v20, v31
	v_mul_f32_e32 v21, v16, v39
	v_fma_f32 v24, -v38, v21, v16
	v_fmac_f32_e32 v21, v24, v39
	v_fma_f32 v16, -v38, v21, v16
	v_div_fmas_f32 v16, v16, v39, v21
	v_pk_mul_f32 v[14:15], v[4:5], v[14:15]
	v_div_fixup_f32 v16, v16, v20, v31
	v_pk_mul_f32 v[20:21], v[14:15], v[16:17]
	v_cvt_pk_bf16_f32 v14, v18, v19
	v_cvt_pk_bf16_f32 v15, v32, v33
	v_cvt_pk_bf16_f32 v16, v34, v35
	v_cvt_pk_bf16_f32 v17, v20, v21
	v_lshl_add_u64 v[18:19], s[36:37], 0, v[26:27]
	global_store_dwordx4 v[18:19], v[14:17], off sc1
	s_waitcnt lgkmcnt(0)
	v_lshlrev_b32_e32 v26, 16, v10
	v_and_b32_e32 v27, 0xffff0000, v10
	v_or_b32_e32 v14, 2, v22
	v_mov_b32_e32 v15, v23
	v_lshlrev_b64 v[18:19], 11, v[14:15]
	v_or_b32_e32 v18, v18, v28
	v_lshl_add_u64 v[14:15], s[60:61], 0, v[18:19]
	v_mov_b32_e32 v10, v25
	v_pk_mul_f32 v[24:25], v[10:11], v[26:27] op_sel_hi:[0,1]
	v_pk_mul_f32 v[24:25], v[6:7], v[24:25]
	v_lshlrev_b32_e32 v31, 16, v64
	v_and_b32_e32 v14, 0xffff0000, v64
	v_mul_f32_e32 v20, 0xbfb8aa3b, v31
	v_mul_f32_e32 v21, 0xbfb8aa3b, v14
	v_exp_f32_e32 v20, v20
	v_exp_f32_e32 v21, v21
	s_nop 0
	v_pk_add_f32 v[20:21], v[20:21], 1.0 op_sel_hi:[1,0]
	s_nop 0
	v_div_scale_f32 v32, s[0:1], v21, v21, v14
	v_rcp_f32_e32 v33, v32
	s_nop 0
	v_fma_f32 v26, -v32, v33, 1.0
	v_fmac_f32_e32 v33, v26, v33
	v_div_scale_f32 v26, vcc, v14, v21, v14
	v_mul_f32_e32 v27, v26, v33
	v_fma_f32 v34, -v32, v27, v26
	v_fmac_f32_e32 v27, v34, v33
	v_fma_f32 v26, -v32, v27, v26
	v_div_scale_f32 v32, s[0:1], v20, v20, v31
	v_rcp_f32_e32 v34, v32
	v_div_fmas_f32 v26, v26, v33, v27
	v_div_fixup_f32 v21, v26, v21, v14
	v_fma_f32 v14, -v32, v34, 1.0
	v_fmac_f32_e32 v34, v14, v34
	v_div_scale_f32 v14, vcc, v31, v20, v31
	v_mul_f32_e32 v26, v14, v34
	v_fma_f32 v27, -v32, v26, v14
	v_fmac_f32_e32 v26, v27, v34
	v_fma_f32 v14, -v32, v26, v14
	v_lshlrev_b32_e32 v32, 16, v65
	v_and_b32_e32 v27, 0xffff0000, v65
	v_div_fmas_f32 v26, v14, v34, v26
	v_mul_f32_e32 v14, 0xbfb8aa3b, v32
	v_mul_f32_e32 v15, 0xbfb8aa3b, v27
	v_exp_f32_e32 v14, v14
	v_exp_f32_e32 v15, v15
	v_div_fixup_f32 v20, v26, v20, v31
	v_pk_mul_f32 v[20:21], v[24:25], v[20:21]
	v_lshlrev_b32_e32 v24, 16, v11
	v_pk_add_f32 v[14:15], v[14:15], 1.0 op_sel_hi:[1,0]
	v_and_b32_e32 v25, 0xffff0000, v11
	v_div_scale_f32 v26, s[0:1], v15, v15, v27
	v_rcp_f32_e32 v31, v26
	v_pk_mul_f32 v[24:25], v[10:11], v[24:25] op_sel_hi:[0,1]
	v_pk_mul_f32 v[24:25], v[8:9], v[24:25]
	v_fma_f32 v11, -v26, v31, 1.0
	v_fmac_f32_e32 v31, v11, v31
	v_div_scale_f32 v11, vcc, v27, v15, v27
	v_mul_f32_e32 v33, v11, v31
	v_fma_f32 v34, -v26, v33, v11
	v_fmac_f32_e32 v33, v34, v31
	v_fma_f32 v11, -v26, v33, v11
	v_div_scale_f32 v26, s[0:1], v14, v14, v32
	v_rcp_f32_e32 v34, v26
	v_div_fmas_f32 v11, v11, v31, v33
	v_div_fixup_f32 v15, v11, v15, v27
	v_fma_f32 v11, -v26, v34, 1.0
	v_fmac_f32_e32 v34, v11, v34
	v_div_scale_f32 v11, vcc, v32, v14, v32
	v_mul_f32_e32 v27, v11, v34
	v_fma_f32 v31, -v26, v27, v11
	v_fmac_f32_e32 v27, v31, v34
	v_fma_f32 v11, -v26, v27, v11
	v_lshlrev_b32_e32 v31, 16, v66
	v_and_b32_e32 v16, 0xffff0000, v66
	v_div_fmas_f32 v11, v11, v34, v27
	v_mul_f32_e32 v26, 0xbfb8aa3b, v31
	v_mul_f32_e32 v27, 0xbfb8aa3b, v16
	v_exp_f32_e32 v26, v26
	v_exp_f32_e32 v27, v27
	v_div_fixup_f32 v14, v11, v14, v32
	v_pk_mul_f32 v[14:15], v[24:25], v[14:15]
	v_lshlrev_b32_e32 v24, 16, v12
	v_pk_add_f32 v[26:27], v[26:27], 1.0 op_sel_hi:[1,0]
	v_and_b32_e32 v25, 0xffff0000, v12
	v_div_scale_f32 v11, s[0:1], v27, v27, v16
	v_rcp_f32_e32 v32, v11
	v_pk_mul_f32 v[24:25], v[10:11], v[24:25] op_sel_hi:[0,1]
	v_pk_mul_f32 v[24:25], v[2:3], v[24:25]
	v_fma_f32 v12, -v11, v32, 1.0
	v_fmac_f32_e32 v32, v12, v32
	v_div_scale_f32 v12, vcc, v16, v27, v16
	v_mul_f32_e32 v33, v12, v32
	v_fma_f32 v34, -v11, v33, v12
	v_fmac_f32_e32 v33, v34, v32
	v_fma_f32 v11, -v11, v33, v12
	v_div_scale_f32 v12, s[0:1], v26, v26, v31
	v_rcp_f32_e32 v34, v12
	v_div_fmas_f32 v11, v11, v32, v33
	v_div_fixup_f32 v27, v11, v27, v16
	v_and_b32_e32 v33, 0xffff0000, v67
	v_fma_f32 v11, -v12, v34, 1.0
	v_fmac_f32_e32 v34, v11, v34
	v_div_scale_f32 v11, vcc, v31, v26, v31
	v_mul_f32_e32 v16, v11, v34
	v_fma_f32 v32, -v12, v16, v11
	v_fmac_f32_e32 v16, v32, v34
	v_lshlrev_b32_e32 v32, 16, v67
	v_fma_f32 v11, -v12, v16, v11
	v_mul_f32_e32 v12, 0xbfb8aa3b, v32
	v_div_fmas_f32 v11, v11, v34, v16
	v_exp_f32_e32 v16, v12
	v_mul_f32_e32 v12, 0xbfb8aa3b, v33
	v_exp_f32_e32 v17, v12
	v_div_fixup_f32 v26, v11, v26, v31
	v_pk_mul_f32 v[24:25], v[24:25], v[26:27]
	v_lshlrev_b32_e32 v12, 16, v13
	v_pk_add_f32 v[16:17], v[16:17], 1.0 op_sel_hi:[1,0]
	v_and_b32_e32 v13, 0xffff0000, v13
	v_div_scale_f32 v26, s[0:1], v17, v17, v33
	v_rcp_f32_e32 v27, v26
	v_pk_mul_f32 v[10:11], v[10:11], v[12:13] op_sel_hi:[0,1]
	v_pk_mul_f32 v[10:11], v[4:5], v[10:11]
	v_fma_f32 v12, -v26, v27, 1.0
	v_fmac_f32_e32 v27, v12, v27
	v_div_scale_f32 v12, vcc, v33, v17, v33
	v_mul_f32_e32 v13, v12, v27
	v_fma_f32 v31, -v26, v13, v12
	v_fmac_f32_e32 v13, v31, v27
	v_fma_f32 v12, -v26, v13, v12
	v_div_scale_f32 v26, s[0:1], v16, v16, v32
	v_rcp_f32_e32 v31, v26
	v_div_fmas_f32 v12, v12, v27, v13
	v_div_fixup_f32 v13, v12, v17, v33
	v_fma_f32 v12, -v26, v31, 1.0
	v_fmac_f32_e32 v31, v12, v31
	v_div_scale_f32 v12, vcc, v32, v16, v32
	v_mul_f32_e32 v17, v12, v31
	v_fma_f32 v27, -v26, v17, v12
	v_fmac_f32_e32 v17, v27, v31
	v_fma_f32 v12, -v26, v17, v12
	v_div_fmas_f32 v12, v12, v31, v17
	v_div_fixup_f32 v12, v12, v16, v32
	v_pk_mul_f32 v[16:17], v[10:11], v[12:13]
	v_cvt_pk_bf16_f32 v10, v20, v21
	v_cvt_pk_bf16_f32 v11, v14, v15
	v_cvt_pk_bf16_f32 v12, v24, v25
	v_cvt_pk_bf16_f32 v13, v16, v17
	v_lshl_add_u64 v[14:15], s[36:37], 0, v[18:19]
	global_store_dwordx4 v[14:15], v[10:13], off sc1
	ds_read_b128 v[14:17], v29 offset:2112
	s_waitcnt lgkmcnt(0)
	v_lshlrev_b32_e32 v34, 16, v14
	v_or_b32_e32 v10, 4, v22
	v_mov_b32_e32 v11, v23
	v_lshlrev_b64 v[26:27], 11, v[10:11]
	v_or_b32_e32 v26, v26, v28
	v_lshl_add_u64 v[10:11], s[60:61], 0, v[26:27]
	v_and_b32_e32 v35, 0xffff0000, v14
	v_lshlrev_b32_e32 v31, 16, v68
	v_and_b32_e32 v18, 0xffff0000, v68
	v_mul_f32_e32 v10, 0xbfb8aa3b, v31
	v_exp_f32_e32 v32, v10
	v_mul_f32_e32 v10, 0xbfb8aa3b, v18
	v_exp_f32_e32 v33, v10
	ds_read2_b32 v[24:25], v30 offset0:132 offset1:134
	ds_read_b128 v[10:13], v29 offset:3168
	v_pk_add_f32 v[32:33], v[32:33], 1.0 op_sel_hi:[1,0]
	s_nop 0
	v_div_scale_f32 v36, s[0:1], v33, v33, v18
	v_rcp_f32_e32 v37, v36
	s_waitcnt lgkmcnt(1)
	v_pk_mul_f32 v[34:35], v[24:25], v[34:35] op_sel_hi:[0,1]
	v_pk_mul_f32 v[34:35], v[6:7], v[34:35]
	v_fma_f32 v14, -v36, v37, 1.0
	v_fmac_f32_e32 v37, v14, v37
	v_div_scale_f32 v14, vcc, v18, v33, v18
	v_mul_f32_e32 v38, v14, v37
	v_fma_f32 v39, -v36, v38, v14
	v_fmac_f32_e32 v38, v39, v37
	v_fma_f32 v14, -v36, v38, v14
	v_div_scale_f32 v36, s[0:1], v32, v32, v31
	v_rcp_f32_e32 v39, v36
	v_div_fmas_f32 v14, v14, v37, v38
	v_div_fixup_f32 v33, v14, v33, v18
	v_fma_f32 v14, -v36, v39, 1.0
	v_fmac_f32_e32 v39, v14, v39
	v_div_scale_f32 v14, vcc, v31, v32, v31
	v_mul_f32_e32 v18, v14, v39
	v_fma_f32 v37, -v36, v18, v14
	v_fmac_f32_e32 v18, v37, v39
	v_fma_f32 v14, -v36, v18, v14
	v_lshlrev_b32_e32 v36, 16, v69
	v_and_b32_e32 v37, 0xffff0000, v69
	v_div_fmas_f32 v14, v14, v39, v18
	v_mul_f32_e32 v18, 0xbfb8aa3b, v36
	v_mul_f32_e32 v19, 0xbfb8aa3b, v37
	v_exp_f32_e32 v18, v18
	v_exp_f32_e32 v19, v19
	v_div_fixup_f32 v32, v14, v32, v31
	v_pk_mul_f32 v[32:33], v[34:35], v[32:33]
	v_lshlrev_b32_e32 v14, 16, v15
	v_pk_add_f32 v[18:19], v[18:19], 1.0 op_sel_hi:[1,0]
	v_and_b32_e32 v15, 0xffff0000, v15
	v_div_scale_f32 v31, s[0:1], v19, v19, v37
	v_rcp_f32_e32 v34, v31
	v_pk_mul_f32 v[14:15], v[24:25], v[14:15] op_sel_hi:[0,1]
	v_pk_mul_f32 v[14:15], v[8:9], v[14:15]
	v_fma_f32 v35, -v31, v34, 1.0
	v_fmac_f32_e32 v34, v35, v34
	v_div_scale_f32 v35, vcc, v37, v19, v37
	v_mul_f32_e32 v38, v35, v34
	v_fma_f32 v39, -v31, v38, v35
	v_fmac_f32_e32 v38, v39, v34
	v_fma_f32 v31, -v31, v38, v35
	v_div_scale_f32 v35, s[0:1], v18, v18, v36
	v_rcp_f32_e32 v39, v35
	v_div_fmas_f32 v31, v31, v34, v38
	v_div_fixup_f32 v19, v31, v19, v37
	v_fma_f32 v31, -v35, v39, 1.0
	v_fmac_f32_e32 v39, v31, v39
	v_div_scale_f32 v31, vcc, v36, v18, v36
	v_mul_f32_e32 v34, v31, v39
	v_fma_f32 v37, -v35, v34, v31
	v_fmac_f32_e32 v34, v37, v39
	v_fma_f32 v31, -v35, v34, v31
	v_lshlrev_b32_e32 v37, 16, v70
	v_and_b32_e32 v20, 0xffff0000, v70
	v_div_fmas_f32 v31, v31, v39, v34
	v_mul_f32_e32 v34, 0xbfb8aa3b, v37
	v_mul_f32_e32 v35, 0xbfb8aa3b, v20
	v_exp_f32_e32 v34, v34
	v_exp_f32_e32 v35, v35
	v_div_fixup_f32 v18, v31, v18, v36
	v_pk_mul_f32 v[18:19], v[14:15], v[18:19]
	v_lshlrev_b32_e32 v14, 16, v16
	v_pk_add_f32 v[34:35], v[34:35], 1.0 op_sel_hi:[1,0]
	v_and_b32_e32 v15, 0xffff0000, v16
	v_div_scale_f32 v31, s[0:1], v35, v35, v20
	v_rcp_f32_e32 v36, v31
	v_pk_mul_f32 v[14:15], v[24:25], v[14:15] op_sel_hi:[0,1]
	v_pk_mul_f32 v[14:15], v[2:3], v[14:15]
	v_fma_f32 v16, -v31, v36, 1.0
	v_fmac_f32_e32 v36, v16, v36
	v_div_scale_f32 v16, vcc, v20, v35, v20
	v_mul_f32_e32 v38, v16, v36
	v_fma_f32 v39, -v31, v38, v16
	v_fmac_f32_e32 v38, v39, v36
	v_fma_f32 v16, -v31, v38, v16
	v_div_scale_f32 v31, s[0:1], v34, v34, v37
	v_rcp_f32_e32 v39, v31
	v_div_fmas_f32 v16, v16, v36, v38
	v_div_fixup_f32 v35, v16, v35, v20
	v_fma_f32 v16, -v31, v39, 1.0
	v_fmac_f32_e32 v39, v16, v39
	v_div_scale_f32 v16, vcc, v37, v34, v37
	v_mul_f32_e32 v20, v16, v39
	v_fma_f32 v36, -v31, v20, v16
	v_fmac_f32_e32 v20, v36, v39
	v_fma_f32 v16, -v31, v20, v16
	v_lshlrev_b32_e32 v31, 16, v71
	v_and_b32_e32 v36, 0xffff0000, v71
	v_div_fmas_f32 v16, v16, v39, v20
	v_mul_f32_e32 v20, 0xbfb8aa3b, v31
	v_mul_f32_e32 v21, 0xbfb8aa3b, v36
	v_exp_f32_e32 v20, v20
	v_exp_f32_e32 v21, v21
	v_div_fixup_f32 v34, v16, v34, v37
	v_pk_mul_f32 v[34:35], v[14:15], v[34:35]
	v_lshlrev_b32_e32 v14, 16, v17
	v_pk_add_f32 v[20:21], v[20:21], 1.0 op_sel_hi:[1,0]
	v_and_b32_e32 v15, 0xffff0000, v17
	v_div_scale_f32 v16, s[0:1], v21, v21, v36
	v_rcp_f32_e32 v37, v16
	v_pk_mul_f32 v[14:15], v[24:25], v[14:15] op_sel_hi:[0,1]
	v_pk_mul_f32 v[14:15], v[4:5], v[14:15]
	v_fma_f32 v17, -v16, v37, 1.0
	v_fmac_f32_e32 v37, v17, v37
	v_div_scale_f32 v17, vcc, v36, v21, v36
	v_mul_f32_e32 v24, v17, v37
	v_fma_f32 v38, -v16, v24, v17
	v_fmac_f32_e32 v24, v38, v37
	v_div_scale_f32 v38, s[0:1], v20, v20, v31
	v_rcp_f32_e32 v39, v38
	v_fma_f32 v16, -v16, v24, v17
	v_div_fmas_f32 v16, v16, v37, v24
	v_div_fixup_f32 v17, v16, v21, v36
	v_fma_f32 v16, -v38, v39, 1.0
	v_fmac_f32_e32 v39, v16, v39
	v_div_scale_f32 v16, vcc, v31, v20, v31
	v_mul_f32_e32 v21, v16, v39
	v_fma_f32 v24, -v38, v21, v16
	v_fmac_f32_e32 v21, v24, v39
	v_fma_f32 v16, -v38, v21, v16
	v_div_fmas_f32 v16, v16, v39, v21
	v_div_fixup_f32 v16, v16, v20, v31
	v_pk_mul_f32 v[20:21], v[14:15], v[16:17]
	v_cvt_pk_bf16_f32 v14, v32, v33
	v_cvt_pk_bf16_f32 v15, v18, v19
	v_cvt_pk_bf16_f32 v16, v34, v35
	v_cvt_pk_bf16_f32 v17, v20, v21
	v_lshl_add_u64 v[18:19], s[36:37], 0, v[26:27]
	global_store_dwordx4 v[18:19], v[14:17], off sc1
	s_waitcnt lgkmcnt(0)
	v_lshlrev_b32_e32 v26, 16, v10
	v_and_b32_e32 v27, 0xffff0000, v10
	v_or_b32_e32 v14, 6, v22
	v_mov_b32_e32 v15, v23
	v_lshlrev_b64 v[18:19], 11, v[14:15]
	v_or_b32_e32 v18, v18, v28
	v_lshl_add_u64 v[14:15], s[60:61], 0, v[18:19]
	v_mov_b32_e32 v10, v25
	v_pk_mul_f32 v[24:25], v[10:11], v[26:27] op_sel_hi:[0,1]
	v_pk_mul_f32 v[24:25], v[6:7], v[24:25]
	v_lshlrev_b32_e32 v31, 16, v72
	v_and_b32_e32 v14, 0xffff0000, v72
	v_mul_f32_e32 v20, 0xbfb8aa3b, v31
	v_mul_f32_e32 v21, 0xbfb8aa3b, v14
	v_exp_f32_e32 v20, v20
	v_exp_f32_e32 v21, v21
	s_nop 0
	v_pk_add_f32 v[20:21], v[20:21], 1.0 op_sel_hi:[1,0]
	s_nop 0
	v_div_scale_f32 v32, s[0:1], v21, v21, v14
	v_rcp_f32_e32 v33, v32
	s_nop 0
	v_fma_f32 v26, -v32, v33, 1.0
	v_fmac_f32_e32 v33, v26, v33
	v_div_scale_f32 v26, vcc, v14, v21, v14
	v_mul_f32_e32 v27, v26, v33
	v_fma_f32 v34, -v32, v27, v26
	v_fmac_f32_e32 v27, v34, v33
	v_fma_f32 v26, -v32, v27, v26
	v_div_scale_f32 v32, s[0:1], v20, v20, v31
	v_rcp_f32_e32 v34, v32
	v_div_fmas_f32 v26, v26, v33, v27
	v_div_fixup_f32 v21, v26, v21, v14
	v_fma_f32 v14, -v32, v34, 1.0
	v_fmac_f32_e32 v34, v14, v34
	v_div_scale_f32 v14, vcc, v31, v20, v31
	v_mul_f32_e32 v26, v14, v34
	v_fma_f32 v27, -v32, v26, v14
	v_fmac_f32_e32 v26, v27, v34
	v_fma_f32 v14, -v32, v26, v14
	v_lshlrev_b32_e32 v32, 16, v73
	v_and_b32_e32 v27, 0xffff0000, v73
	v_div_fmas_f32 v26, v14, v34, v26
	v_mul_f32_e32 v14, 0xbfb8aa3b, v32
	v_mul_f32_e32 v15, 0xbfb8aa3b, v27
	v_exp_f32_e32 v14, v14
	v_exp_f32_e32 v15, v15
	v_div_fixup_f32 v20, v26, v20, v31
	v_pk_mul_f32 v[20:21], v[24:25], v[20:21]
	v_lshlrev_b32_e32 v24, 16, v11
	v_pk_add_f32 v[14:15], v[14:15], 1.0 op_sel_hi:[1,0]
	v_and_b32_e32 v25, 0xffff0000, v11
	v_div_scale_f32 v26, s[0:1], v15, v15, v27
	v_rcp_f32_e32 v31, v26
	v_pk_mul_f32 v[24:25], v[10:11], v[24:25] op_sel_hi:[0,1]
	v_pk_mul_f32 v[24:25], v[8:9], v[24:25]
	v_fma_f32 v11, -v26, v31, 1.0
	v_fmac_f32_e32 v31, v11, v31
	v_div_scale_f32 v11, vcc, v27, v15, v27
	v_mul_f32_e32 v33, v11, v31
	v_fma_f32 v34, -v26, v33, v11
	v_fmac_f32_e32 v33, v34, v31
	v_fma_f32 v11, -v26, v33, v11
	v_div_scale_f32 v26, s[0:1], v14, v14, v32
	v_rcp_f32_e32 v34, v26
	v_div_fmas_f32 v11, v11, v31, v33
	v_div_fixup_f32 v15, v11, v15, v27
	v_fma_f32 v11, -v26, v34, 1.0
	v_fmac_f32_e32 v34, v11, v34
	v_div_scale_f32 v11, vcc, v32, v14, v32
	v_mul_f32_e32 v27, v11, v34
	v_fma_f32 v31, -v26, v27, v11
	v_fmac_f32_e32 v27, v31, v34
	v_fma_f32 v11, -v26, v27, v11
	v_lshlrev_b32_e32 v31, 16, v74
	v_and_b32_e32 v16, 0xffff0000, v74
	v_div_fmas_f32 v11, v11, v34, v27
	v_mul_f32_e32 v26, 0xbfb8aa3b, v31
	v_mul_f32_e32 v27, 0xbfb8aa3b, v16
	v_exp_f32_e32 v26, v26
	v_exp_f32_e32 v27, v27
	v_div_fixup_f32 v14, v11, v14, v32
	v_pk_mul_f32 v[14:15], v[24:25], v[14:15]
	v_lshlrev_b32_e32 v24, 16, v12
	v_pk_add_f32 v[26:27], v[26:27], 1.0 op_sel_hi:[1,0]
	v_and_b32_e32 v25, 0xffff0000, v12
	v_div_scale_f32 v11, s[0:1], v27, v27, v16
	v_rcp_f32_e32 v32, v11
	v_pk_mul_f32 v[24:25], v[10:11], v[24:25] op_sel_hi:[0,1]
	v_pk_mul_f32 v[24:25], v[2:3], v[24:25]
	v_fma_f32 v12, -v11, v32, 1.0
	v_fmac_f32_e32 v32, v12, v32
	v_div_scale_f32 v12, vcc, v16, v27, v16
	v_mul_f32_e32 v33, v12, v32
	v_fma_f32 v34, -v11, v33, v12
	v_fmac_f32_e32 v33, v34, v32
	v_fma_f32 v11, -v11, v33, v12
	v_div_scale_f32 v12, s[0:1], v26, v26, v31
	v_rcp_f32_e32 v34, v12
	v_div_fmas_f32 v11, v11, v32, v33
	v_div_fixup_f32 v27, v11, v27, v16
	v_and_b32_e32 v33, 0xffff0000, v75
	v_fma_f32 v11, -v12, v34, 1.0
	v_fmac_f32_e32 v34, v11, v34
	v_div_scale_f32 v11, vcc, v31, v26, v31
	v_mul_f32_e32 v16, v11, v34
	v_fma_f32 v32, -v12, v16, v11
	v_fmac_f32_e32 v16, v32, v34
	v_lshlrev_b32_e32 v32, 16, v75
	v_fma_f32 v11, -v12, v16, v11
	v_mul_f32_e32 v12, 0xbfb8aa3b, v32
	v_div_fmas_f32 v11, v11, v34, v16
	v_exp_f32_e32 v16, v12
	v_mul_f32_e32 v12, 0xbfb8aa3b, v33
	v_exp_f32_e32 v17, v12
	v_div_fixup_f32 v26, v11, v26, v31
	v_pk_mul_f32 v[24:25], v[24:25], v[26:27]
	v_lshlrev_b32_e32 v12, 16, v13
	v_pk_add_f32 v[16:17], v[16:17], 1.0 op_sel_hi:[1,0]
	v_and_b32_e32 v13, 0xffff0000, v13
	v_div_scale_f32 v26, s[0:1], v17, v17, v33
	v_rcp_f32_e32 v27, v26
	v_pk_mul_f32 v[10:11], v[10:11], v[12:13] op_sel_hi:[0,1]
	v_pk_mul_f32 v[10:11], v[4:5], v[10:11]
	v_fma_f32 v12, -v26, v27, 1.0
	v_fmac_f32_e32 v27, v12, v27
	v_div_scale_f32 v12, vcc, v33, v17, v33
	v_mul_f32_e32 v13, v12, v27
	v_fma_f32 v31, -v26, v13, v12
	v_fmac_f32_e32 v13, v31, v27
	v_fma_f32 v12, -v26, v13, v12
	v_div_scale_f32 v26, s[0:1], v16, v16, v32
	v_rcp_f32_e32 v31, v26
	v_div_fmas_f32 v12, v12, v27, v13
	v_div_fixup_f32 v13, v12, v17, v33
	v_fma_f32 v12, -v26, v31, 1.0
	v_fmac_f32_e32 v31, v12, v31
	v_div_scale_f32 v12, vcc, v32, v16, v32
	v_mul_f32_e32 v17, v12, v31
	v_fma_f32 v27, -v26, v17, v12
	v_fmac_f32_e32 v17, v27, v31
	v_fma_f32 v12, -v26, v17, v12
	v_div_fmas_f32 v12, v12, v31, v17
	v_div_fixup_f32 v12, v12, v16, v32
	v_pk_mul_f32 v[16:17], v[10:11], v[12:13]
	v_cvt_pk_bf16_f32 v10, v20, v21
	v_cvt_pk_bf16_f32 v11, v14, v15
	v_cvt_pk_bf16_f32 v12, v24, v25
	v_cvt_pk_bf16_f32 v13, v16, v17
	v_lshl_add_u64 v[14:15], s[36:37], 0, v[18:19]
	global_store_dwordx4 v[14:15], v[10:13], off sc1
	ds_read_b128 v[14:17], v29 offset:4224
	s_waitcnt lgkmcnt(0)
	v_lshlrev_b32_e32 v34, 16, v14
	v_or_b32_e32 v10, 8, v22
	v_mov_b32_e32 v11, v23
	v_lshlrev_b64 v[26:27], 11, v[10:11]
	v_or_b32_e32 v26, v26, v28
	v_lshl_add_u64 v[10:11], s[60:61], 0, v[26:27]
	v_and_b32_e32 v35, 0xffff0000, v14
	v_lshlrev_b32_e32 v31, 16, v76
	v_and_b32_e32 v18, 0xffff0000, v76
	v_mul_f32_e32 v10, 0xbfb8aa3b, v31
	v_exp_f32_e32 v32, v10
	v_mul_f32_e32 v10, 0xbfb8aa3b, v18
	v_exp_f32_e32 v33, v10
	ds_read2_b32 v[24:25], v30 offset0:136 offset1:138
	ds_read_b128 v[10:13], v29 offset:5280
	v_pk_add_f32 v[32:33], v[32:33], 1.0 op_sel_hi:[1,0]
	s_nop 0
	v_div_scale_f32 v36, s[0:1], v33, v33, v18
	v_rcp_f32_e32 v37, v36
	s_waitcnt lgkmcnt(1)
	v_pk_mul_f32 v[34:35], v[24:25], v[34:35] op_sel_hi:[0,1]
	v_pk_mul_f32 v[34:35], v[6:7], v[34:35]
	v_fma_f32 v14, -v36, v37, 1.0
	v_fmac_f32_e32 v37, v14, v37
	v_div_scale_f32 v14, vcc, v18, v33, v18
	v_mul_f32_e32 v38, v14, v37
	v_fma_f32 v39, -v36, v38, v14
	v_fmac_f32_e32 v38, v39, v37
	v_fma_f32 v14, -v36, v38, v14
	v_div_scale_f32 v36, s[0:1], v32, v32, v31
	v_rcp_f32_e32 v39, v36
	v_div_fmas_f32 v14, v14, v37, v38
	v_div_fixup_f32 v33, v14, v33, v18
	v_fma_f32 v14, -v36, v39, 1.0
	v_fmac_f32_e32 v39, v14, v39
	v_div_scale_f32 v14, vcc, v31, v32, v31
	v_mul_f32_e32 v18, v14, v39
	v_fma_f32 v37, -v36, v18, v14
	v_fmac_f32_e32 v18, v37, v39
	v_fma_f32 v14, -v36, v18, v14
	v_lshlrev_b32_e32 v36, 16, v77
	v_and_b32_e32 v37, 0xffff0000, v77
	v_div_fmas_f32 v14, v14, v39, v18
	v_mul_f32_e32 v18, 0xbfb8aa3b, v36
	v_mul_f32_e32 v19, 0xbfb8aa3b, v37
	v_exp_f32_e32 v18, v18
	v_exp_f32_e32 v19, v19
	v_div_fixup_f32 v32, v14, v32, v31
	v_pk_mul_f32 v[32:33], v[34:35], v[32:33]
	v_lshlrev_b32_e32 v14, 16, v15
	v_pk_add_f32 v[18:19], v[18:19], 1.0 op_sel_hi:[1,0]
	v_and_b32_e32 v15, 0xffff0000, v15
	v_div_scale_f32 v31, s[0:1], v19, v19, v37
	v_rcp_f32_e32 v34, v31
	v_pk_mul_f32 v[14:15], v[24:25], v[14:15] op_sel_hi:[0,1]
	v_pk_mul_f32 v[14:15], v[8:9], v[14:15]
	v_fma_f32 v35, -v31, v34, 1.0
	v_fmac_f32_e32 v34, v35, v34
	v_div_scale_f32 v35, vcc, v37, v19, v37
	v_mul_f32_e32 v38, v35, v34
	v_fma_f32 v39, -v31, v38, v35
	v_fmac_f32_e32 v38, v39, v34
	v_fma_f32 v31, -v31, v38, v35
	v_div_scale_f32 v35, s[0:1], v18, v18, v36
	v_rcp_f32_e32 v39, v35
	v_div_fmas_f32 v31, v31, v34, v38
	v_div_fixup_f32 v19, v31, v19, v37
	v_fma_f32 v31, -v35, v39, 1.0
	v_fmac_f32_e32 v39, v31, v39
	v_div_scale_f32 v31, vcc, v36, v18, v36
	v_mul_f32_e32 v34, v31, v39
	v_fma_f32 v37, -v35, v34, v31
	v_fmac_f32_e32 v34, v37, v39
	v_fma_f32 v31, -v35, v34, v31
	v_lshlrev_b32_e32 v37, 16, v78
	v_and_b32_e32 v20, 0xffff0000, v78
	v_div_fmas_f32 v31, v31, v39, v34
	v_mul_f32_e32 v34, 0xbfb8aa3b, v37
	v_mul_f32_e32 v35, 0xbfb8aa3b, v20
	v_exp_f32_e32 v34, v34
	v_exp_f32_e32 v35, v35
	v_div_fixup_f32 v18, v31, v18, v36
	v_pk_mul_f32 v[18:19], v[14:15], v[18:19]
	v_lshlrev_b32_e32 v14, 16, v16
	v_pk_add_f32 v[34:35], v[34:35], 1.0 op_sel_hi:[1,0]
	v_and_b32_e32 v15, 0xffff0000, v16
	v_div_scale_f32 v31, s[0:1], v35, v35, v20
	v_rcp_f32_e32 v36, v31
	v_pk_mul_f32 v[14:15], v[24:25], v[14:15] op_sel_hi:[0,1]
	v_pk_mul_f32 v[14:15], v[2:3], v[14:15]
	v_fma_f32 v16, -v31, v36, 1.0
	v_fmac_f32_e32 v36, v16, v36
	v_div_scale_f32 v16, vcc, v20, v35, v20
	v_mul_f32_e32 v38, v16, v36
	v_fma_f32 v39, -v31, v38, v16
	v_fmac_f32_e32 v38, v39, v36
	v_fma_f32 v16, -v31, v38, v16
	v_div_scale_f32 v31, s[0:1], v34, v34, v37
	v_rcp_f32_e32 v39, v31
	v_div_fmas_f32 v16, v16, v36, v38
	v_div_fixup_f32 v35, v16, v35, v20
	v_fma_f32 v16, -v31, v39, 1.0
	v_fmac_f32_e32 v39, v16, v39
	v_div_scale_f32 v16, vcc, v37, v34, v37
	v_mul_f32_e32 v20, v16, v39
	v_fma_f32 v36, -v31, v20, v16
	v_fmac_f32_e32 v20, v36, v39
	v_fma_f32 v16, -v31, v20, v16
	v_lshlrev_b32_e32 v31, 16, v79
	v_and_b32_e32 v36, 0xffff0000, v79
	v_div_fmas_f32 v16, v16, v39, v20
	v_mul_f32_e32 v20, 0xbfb8aa3b, v31
	v_mul_f32_e32 v21, 0xbfb8aa3b, v36
	v_exp_f32_e32 v20, v20
	v_exp_f32_e32 v21, v21
	v_div_fixup_f32 v34, v16, v34, v37
	v_pk_mul_f32 v[34:35], v[14:15], v[34:35]
	v_lshlrev_b32_e32 v14, 16, v17
	v_pk_add_f32 v[20:21], v[20:21], 1.0 op_sel_hi:[1,0]
	v_and_b32_e32 v15, 0xffff0000, v17
	v_div_scale_f32 v16, s[0:1], v21, v21, v36
	v_rcp_f32_e32 v37, v16
	v_pk_mul_f32 v[14:15], v[24:25], v[14:15] op_sel_hi:[0,1]
	v_pk_mul_f32 v[14:15], v[4:5], v[14:15]
	v_fma_f32 v17, -v16, v37, 1.0
	v_fmac_f32_e32 v37, v17, v37
	v_div_scale_f32 v17, vcc, v36, v21, v36
	v_mul_f32_e32 v24, v17, v37
	v_fma_f32 v38, -v16, v24, v17
	v_fmac_f32_e32 v24, v38, v37
	v_div_scale_f32 v38, s[0:1], v20, v20, v31
	v_rcp_f32_e32 v39, v38
	v_fma_f32 v16, -v16, v24, v17
	v_div_fmas_f32 v16, v16, v37, v24
	v_div_fixup_f32 v17, v16, v21, v36
	v_fma_f32 v16, -v38, v39, 1.0
	v_fmac_f32_e32 v39, v16, v39
	v_div_scale_f32 v16, vcc, v31, v20, v31
	v_mul_f32_e32 v21, v16, v39
	v_fma_f32 v24, -v38, v21, v16
	v_fmac_f32_e32 v21, v24, v39
	v_fma_f32 v16, -v38, v21, v16
	v_div_fmas_f32 v16, v16, v39, v21
	v_div_fixup_f32 v16, v16, v20, v31
	v_pk_mul_f32 v[20:21], v[14:15], v[16:17]
	v_cvt_pk_bf16_f32 v14, v32, v33
	v_cvt_pk_bf16_f32 v15, v18, v19
	v_cvt_pk_bf16_f32 v16, v34, v35
	v_cvt_pk_bf16_f32 v17, v20, v21
	v_lshl_add_u64 v[18:19], s[36:37], 0, v[26:27]
	global_store_dwordx4 v[18:19], v[14:17], off sc1
	s_waitcnt lgkmcnt(0)
	v_lshlrev_b32_e32 v26, 16, v10
	v_and_b32_e32 v27, 0xffff0000, v10
	v_or_b32_e32 v14, 10, v22
	v_mov_b32_e32 v15, v23
	v_lshlrev_b64 v[18:19], 11, v[14:15]
	v_or_b32_e32 v18, v18, v28
	v_lshl_add_u64 v[14:15], s[60:61], 0, v[18:19]
	v_mov_b32_e32 v10, v25
	v_pk_mul_f32 v[24:25], v[10:11], v[26:27] op_sel_hi:[0,1]
	v_pk_mul_f32 v[24:25], v[6:7], v[24:25]
	v_lshlrev_b32_e32 v31, 16, v80
	v_and_b32_e32 v14, 0xffff0000, v80
	v_mul_f32_e32 v20, 0xbfb8aa3b, v31
	v_mul_f32_e32 v21, 0xbfb8aa3b, v14
	v_exp_f32_e32 v20, v20
	v_exp_f32_e32 v21, v21
	s_nop 0
	v_pk_add_f32 v[20:21], v[20:21], 1.0 op_sel_hi:[1,0]
	s_nop 0
	v_div_scale_f32 v32, s[0:1], v21, v21, v14
	v_rcp_f32_e32 v33, v32
	s_nop 0
	v_fma_f32 v26, -v32, v33, 1.0
	v_fmac_f32_e32 v33, v26, v33
	v_div_scale_f32 v26, vcc, v14, v21, v14
	v_mul_f32_e32 v27, v26, v33
	v_fma_f32 v34, -v32, v27, v26
	v_fmac_f32_e32 v27, v34, v33
	v_fma_f32 v26, -v32, v27, v26
	v_div_scale_f32 v32, s[0:1], v20, v20, v31
	v_rcp_f32_e32 v34, v32
	v_div_fmas_f32 v26, v26, v33, v27
	v_div_fixup_f32 v21, v26, v21, v14
	v_fma_f32 v14, -v32, v34, 1.0
	v_fmac_f32_e32 v34, v14, v34
	v_div_scale_f32 v14, vcc, v31, v20, v31
	v_mul_f32_e32 v26, v14, v34
	v_fma_f32 v27, -v32, v26, v14
	v_fmac_f32_e32 v26, v27, v34
	v_fma_f32 v14, -v32, v26, v14
	v_lshlrev_b32_e32 v32, 16, v81
	v_and_b32_e32 v27, 0xffff0000, v81
	v_div_fmas_f32 v26, v14, v34, v26
	v_mul_f32_e32 v14, 0xbfb8aa3b, v32
	v_mul_f32_e32 v15, 0xbfb8aa3b, v27
	v_exp_f32_e32 v14, v14
	v_exp_f32_e32 v15, v15
	v_div_fixup_f32 v20, v26, v20, v31
	v_pk_mul_f32 v[20:21], v[24:25], v[20:21]
	v_lshlrev_b32_e32 v24, 16, v11
	v_pk_add_f32 v[14:15], v[14:15], 1.0 op_sel_hi:[1,0]
	v_and_b32_e32 v25, 0xffff0000, v11
	v_div_scale_f32 v26, s[0:1], v15, v15, v27
	v_rcp_f32_e32 v31, v26
	v_pk_mul_f32 v[24:25], v[10:11], v[24:25] op_sel_hi:[0,1]
	v_pk_mul_f32 v[24:25], v[8:9], v[24:25]
	v_fma_f32 v11, -v26, v31, 1.0
	v_fmac_f32_e32 v31, v11, v31
	v_div_scale_f32 v11, vcc, v27, v15, v27
	v_mul_f32_e32 v33, v11, v31
	v_fma_f32 v34, -v26, v33, v11
	v_fmac_f32_e32 v33, v34, v31
	v_fma_f32 v11, -v26, v33, v11
	v_div_scale_f32 v26, s[0:1], v14, v14, v32
	v_rcp_f32_e32 v34, v26
	v_div_fmas_f32 v11, v11, v31, v33
	v_div_fixup_f32 v15, v11, v15, v27
	v_fma_f32 v11, -v26, v34, 1.0
	v_fmac_f32_e32 v34, v11, v34
	v_div_scale_f32 v11, vcc, v32, v14, v32
	v_mul_f32_e32 v27, v11, v34
	v_fma_f32 v31, -v26, v27, v11
	v_fmac_f32_e32 v27, v31, v34
	v_fma_f32 v11, -v26, v27, v11
	v_lshlrev_b32_e32 v31, 16, v82
	v_and_b32_e32 v16, 0xffff0000, v82
	v_div_fmas_f32 v11, v11, v34, v27
	v_mul_f32_e32 v26, 0xbfb8aa3b, v31
	v_mul_f32_e32 v27, 0xbfb8aa3b, v16
	v_exp_f32_e32 v26, v26
	v_exp_f32_e32 v27, v27
	v_div_fixup_f32 v14, v11, v14, v32
	v_pk_mul_f32 v[14:15], v[24:25], v[14:15]
	v_lshlrev_b32_e32 v24, 16, v12
	v_pk_add_f32 v[26:27], v[26:27], 1.0 op_sel_hi:[1,0]
	v_and_b32_e32 v25, 0xffff0000, v12
	v_div_scale_f32 v11, s[0:1], v27, v27, v16
	v_rcp_f32_e32 v32, v11
	v_pk_mul_f32 v[24:25], v[10:11], v[24:25] op_sel_hi:[0,1]
	v_pk_mul_f32 v[24:25], v[2:3], v[24:25]
	v_fma_f32 v12, -v11, v32, 1.0
	v_fmac_f32_e32 v32, v12, v32
	v_div_scale_f32 v12, vcc, v16, v27, v16
	v_mul_f32_e32 v33, v12, v32
	v_fma_f32 v34, -v11, v33, v12
	v_fmac_f32_e32 v33, v34, v32
	v_fma_f32 v11, -v11, v33, v12
	v_div_scale_f32 v12, s[0:1], v26, v26, v31
	v_rcp_f32_e32 v34, v12
	v_div_fmas_f32 v11, v11, v32, v33
	v_div_fixup_f32 v27, v11, v27, v16
	v_and_b32_e32 v33, 0xffff0000, v83
	v_fma_f32 v11, -v12, v34, 1.0
	v_fmac_f32_e32 v34, v11, v34
	v_div_scale_f32 v11, vcc, v31, v26, v31
	v_mul_f32_e32 v16, v11, v34
	v_fma_f32 v32, -v12, v16, v11
	v_fmac_f32_e32 v16, v32, v34
	v_lshlrev_b32_e32 v32, 16, v83
	v_fma_f32 v11, -v12, v16, v11
	v_mul_f32_e32 v12, 0xbfb8aa3b, v32
	v_div_fmas_f32 v11, v11, v34, v16
	v_exp_f32_e32 v16, v12
	v_mul_f32_e32 v12, 0xbfb8aa3b, v33
	v_exp_f32_e32 v17, v12
	v_div_fixup_f32 v26, v11, v26, v31
	v_pk_mul_f32 v[24:25], v[24:25], v[26:27]
	v_lshlrev_b32_e32 v12, 16, v13
	v_pk_add_f32 v[16:17], v[16:17], 1.0 op_sel_hi:[1,0]
	v_and_b32_e32 v13, 0xffff0000, v13
	v_div_scale_f32 v26, s[0:1], v17, v17, v33
	v_rcp_f32_e32 v27, v26
	v_pk_mul_f32 v[10:11], v[10:11], v[12:13] op_sel_hi:[0,1]
	v_pk_mul_f32 v[10:11], v[4:5], v[10:11]
	v_fma_f32 v12, -v26, v27, 1.0
	v_fmac_f32_e32 v27, v12, v27
	v_div_scale_f32 v12, vcc, v33, v17, v33
	v_mul_f32_e32 v13, v12, v27
	v_fma_f32 v31, -v26, v13, v12
	v_fmac_f32_e32 v13, v31, v27
	v_fma_f32 v12, -v26, v13, v12
	v_div_scale_f32 v26, s[0:1], v16, v16, v32
	v_rcp_f32_e32 v31, v26
	v_div_fmas_f32 v12, v12, v27, v13
	v_div_fixup_f32 v13, v12, v17, v33
	v_fma_f32 v12, -v26, v31, 1.0
	v_fmac_f32_e32 v31, v12, v31
	v_div_scale_f32 v12, vcc, v32, v16, v32
	v_mul_f32_e32 v17, v12, v31
	v_fma_f32 v27, -v26, v17, v12
	v_fmac_f32_e32 v17, v27, v31
	v_fma_f32 v12, -v26, v17, v12
	v_div_fmas_f32 v12, v12, v31, v17
	v_div_fixup_f32 v12, v12, v16, v32
	v_pk_mul_f32 v[16:17], v[10:11], v[12:13]
	v_cvt_pk_bf16_f32 v10, v20, v21
	v_cvt_pk_bf16_f32 v11, v14, v15
	v_cvt_pk_bf16_f32 v12, v24, v25
	v_cvt_pk_bf16_f32 v13, v16, v17
	v_lshl_add_u64 v[14:15], s[36:37], 0, v[18:19]
	global_store_dwordx4 v[14:15], v[10:13], off sc1
	ds_read_b128 v[14:17], v29 offset:6336
	s_waitcnt lgkmcnt(0)
	v_lshlrev_b32_e32 v34, 16, v14
	v_or_b32_e32 v10, 12, v22
	v_mov_b32_e32 v11, v23
	v_lshlrev_b64 v[26:27], 11, v[10:11]
	v_or_b32_e32 v26, v26, v28
	v_lshl_add_u64 v[10:11], s[60:61], 0, v[26:27]
	v_and_b32_e32 v35, 0xffff0000, v14
	v_lshlrev_b32_e32 v31, 16, v84
	v_and_b32_e32 v18, 0xffff0000, v84
	v_mul_f32_e32 v10, 0xbfb8aa3b, v31
	v_exp_f32_e32 v32, v10
	v_mul_f32_e32 v10, 0xbfb8aa3b, v18
	v_exp_f32_e32 v33, v10
	ds_read2_b32 v[24:25], v30 offset0:140 offset1:142
	ds_read_b128 v[10:13], v29 offset:7392
	v_pk_add_f32 v[32:33], v[32:33], 1.0 op_sel_hi:[1,0]
	s_nop 0
	v_div_scale_f32 v36, s[0:1], v33, v33, v18
	v_rcp_f32_e32 v37, v36
	s_waitcnt lgkmcnt(1)
	v_pk_mul_f32 v[34:35], v[24:25], v[34:35] op_sel_hi:[0,1]
	v_pk_mul_f32 v[34:35], v[6:7], v[34:35]
	v_fma_f32 v14, -v36, v37, 1.0
	v_fmac_f32_e32 v37, v14, v37
	v_div_scale_f32 v14, vcc, v18, v33, v18
	v_mul_f32_e32 v38, v14, v37
	v_fma_f32 v39, -v36, v38, v14
	v_fmac_f32_e32 v38, v39, v37
	v_fma_f32 v14, -v36, v38, v14
	v_div_scale_f32 v36, s[0:1], v32, v32, v31
	v_rcp_f32_e32 v39, v36
	v_div_fmas_f32 v14, v14, v37, v38
	v_div_fixup_f32 v33, v14, v33, v18
	v_fma_f32 v14, -v36, v39, 1.0
	v_fmac_f32_e32 v39, v14, v39
	v_div_scale_f32 v14, vcc, v31, v32, v31
	v_mul_f32_e32 v18, v14, v39
	v_fma_f32 v37, -v36, v18, v14
	v_fmac_f32_e32 v18, v37, v39
	v_fma_f32 v14, -v36, v18, v14
	v_lshlrev_b32_e32 v36, 16, v85
	v_and_b32_e32 v37, 0xffff0000, v85
	v_div_fmas_f32 v14, v14, v39, v18
	v_mul_f32_e32 v18, 0xbfb8aa3b, v36
	v_mul_f32_e32 v19, 0xbfb8aa3b, v37
	v_exp_f32_e32 v18, v18
	v_exp_f32_e32 v19, v19
	v_div_fixup_f32 v32, v14, v32, v31
	v_pk_mul_f32 v[32:33], v[34:35], v[32:33]
	v_lshlrev_b32_e32 v14, 16, v15
	v_pk_add_f32 v[18:19], v[18:19], 1.0 op_sel_hi:[1,0]
	v_and_b32_e32 v15, 0xffff0000, v15
	v_div_scale_f32 v31, s[0:1], v19, v19, v37
	v_rcp_f32_e32 v34, v31
	v_pk_mul_f32 v[14:15], v[24:25], v[14:15] op_sel_hi:[0,1]
	v_pk_mul_f32 v[14:15], v[8:9], v[14:15]
	v_fma_f32 v35, -v31, v34, 1.0
	v_fmac_f32_e32 v34, v35, v34
	v_div_scale_f32 v35, vcc, v37, v19, v37
	v_mul_f32_e32 v38, v35, v34
	v_fma_f32 v39, -v31, v38, v35
	v_fmac_f32_e32 v38, v39, v34
	v_fma_f32 v31, -v31, v38, v35
	v_div_scale_f32 v35, s[0:1], v18, v18, v36
	v_rcp_f32_e32 v39, v35
	v_div_fmas_f32 v31, v31, v34, v38
	v_div_fixup_f32 v19, v31, v19, v37
	v_fma_f32 v31, -v35, v39, 1.0
	v_fmac_f32_e32 v39, v31, v39
	v_div_scale_f32 v31, vcc, v36, v18, v36
	v_mul_f32_e32 v34, v31, v39
	v_fma_f32 v37, -v35, v34, v31
	v_fmac_f32_e32 v34, v37, v39
	v_fma_f32 v31, -v35, v34, v31
	v_lshlrev_b32_e32 v37, 16, v86
	v_and_b32_e32 v20, 0xffff0000, v86
	v_div_fmas_f32 v31, v31, v39, v34
	v_mul_f32_e32 v34, 0xbfb8aa3b, v37
	v_mul_f32_e32 v35, 0xbfb8aa3b, v20
	v_exp_f32_e32 v34, v34
	v_exp_f32_e32 v35, v35
	v_div_fixup_f32 v18, v31, v18, v36
	v_pk_mul_f32 v[18:19], v[14:15], v[18:19]
	v_lshlrev_b32_e32 v14, 16, v16
	v_pk_add_f32 v[34:35], v[34:35], 1.0 op_sel_hi:[1,0]
	v_and_b32_e32 v15, 0xffff0000, v16
	v_div_scale_f32 v31, s[0:1], v35, v35, v20
	v_rcp_f32_e32 v36, v31
	v_pk_mul_f32 v[14:15], v[24:25], v[14:15] op_sel_hi:[0,1]
	v_pk_mul_f32 v[14:15], v[2:3], v[14:15]
	v_fma_f32 v16, -v31, v36, 1.0
	v_fmac_f32_e32 v36, v16, v36
	v_div_scale_f32 v16, vcc, v20, v35, v20
	v_mul_f32_e32 v38, v16, v36
	v_fma_f32 v39, -v31, v38, v16
	v_fmac_f32_e32 v38, v39, v36
	v_fma_f32 v16, -v31, v38, v16
	v_div_scale_f32 v31, s[0:1], v34, v34, v37
	v_rcp_f32_e32 v39, v31
	v_div_fmas_f32 v16, v16, v36, v38
	v_div_fixup_f32 v35, v16, v35, v20
	v_fma_f32 v16, -v31, v39, 1.0
	v_fmac_f32_e32 v39, v16, v39
	v_div_scale_f32 v16, vcc, v37, v34, v37
	v_mul_f32_e32 v20, v16, v39
	v_fma_f32 v36, -v31, v20, v16
	v_fmac_f32_e32 v20, v36, v39
	v_fma_f32 v16, -v31, v20, v16
	v_lshlrev_b32_e32 v31, 16, v87
	v_and_b32_e32 v36, 0xffff0000, v87
	v_div_fmas_f32 v16, v16, v39, v20
	v_mul_f32_e32 v20, 0xbfb8aa3b, v31
	v_mul_f32_e32 v21, 0xbfb8aa3b, v36
	v_exp_f32_e32 v20, v20
	v_exp_f32_e32 v21, v21
	v_div_fixup_f32 v34, v16, v34, v37
	v_pk_mul_f32 v[34:35], v[14:15], v[34:35]
	v_lshlrev_b32_e32 v14, 16, v17
	v_pk_add_f32 v[20:21], v[20:21], 1.0 op_sel_hi:[1,0]
	v_and_b32_e32 v15, 0xffff0000, v17
	v_div_scale_f32 v16, s[0:1], v21, v21, v36
	v_rcp_f32_e32 v37, v16
	v_pk_mul_f32 v[14:15], v[24:25], v[14:15] op_sel_hi:[0,1]
	v_pk_mul_f32 v[14:15], v[4:5], v[14:15]
	v_fma_f32 v17, -v16, v37, 1.0
	v_fmac_f32_e32 v37, v17, v37
	v_div_scale_f32 v17, vcc, v36, v21, v36
	v_mul_f32_e32 v24, v17, v37
	v_fma_f32 v38, -v16, v24, v17
	v_fmac_f32_e32 v24, v38, v37
	v_div_scale_f32 v38, s[0:1], v20, v20, v31
	v_rcp_f32_e32 v39, v38
	v_fma_f32 v16, -v16, v24, v17
	v_div_fmas_f32 v16, v16, v37, v24
	v_div_fixup_f32 v17, v16, v21, v36
	v_fma_f32 v16, -v38, v39, 1.0
	v_fmac_f32_e32 v39, v16, v39
	v_div_scale_f32 v16, vcc, v31, v20, v31
	v_mul_f32_e32 v21, v16, v39
	v_fma_f32 v24, -v38, v21, v16
	v_fmac_f32_e32 v21, v24, v39
	v_fma_f32 v16, -v38, v21, v16
	v_div_fmas_f32 v16, v16, v39, v21
	v_div_fixup_f32 v16, v16, v20, v31
	v_pk_mul_f32 v[20:21], v[14:15], v[16:17]
	v_cvt_pk_bf16_f32 v14, v32, v33
	v_cvt_pk_bf16_f32 v15, v18, v19
	v_cvt_pk_bf16_f32 v16, v34, v35
	v_cvt_pk_bf16_f32 v17, v20, v21
	v_lshl_add_u64 v[18:19], s[36:37], 0, v[26:27]
	global_store_dwordx4 v[18:19], v[14:17], off sc1
	s_waitcnt lgkmcnt(0)
	v_lshlrev_b32_e32 v26, 16, v10
	v_and_b32_e32 v27, 0xffff0000, v10
	v_or_b32_e32 v14, 14, v22
	v_mov_b32_e32 v15, v23
	v_lshlrev_b64 v[18:19], 11, v[14:15]
	v_or_b32_e32 v18, v18, v28
	v_lshl_add_u64 v[14:15], s[60:61], 0, v[18:19]
	v_mov_b32_e32 v10, v25
	v_pk_mul_f32 v[24:25], v[10:11], v[26:27] op_sel_hi:[0,1]
	v_pk_mul_f32 v[24:25], v[6:7], v[24:25]
	v_lshlrev_b32_e32 v31, 16, v88
	v_and_b32_e32 v14, 0xffff0000, v88
	v_mul_f32_e32 v20, 0xbfb8aa3b, v31
	v_mul_f32_e32 v21, 0xbfb8aa3b, v14
	v_exp_f32_e32 v20, v20
	v_exp_f32_e32 v21, v21
	s_nop 0
	v_pk_add_f32 v[20:21], v[20:21], 1.0 op_sel_hi:[1,0]
	s_nop 0
	v_div_scale_f32 v32, s[0:1], v21, v21, v14
	v_rcp_f32_e32 v33, v32
	s_nop 0
	v_fma_f32 v26, -v32, v33, 1.0
	v_fmac_f32_e32 v33, v26, v33
	v_div_scale_f32 v26, vcc, v14, v21, v14
	v_mul_f32_e32 v27, v26, v33
	v_fma_f32 v34, -v32, v27, v26
	v_fmac_f32_e32 v27, v34, v33
	v_fma_f32 v26, -v32, v27, v26
	v_div_scale_f32 v32, s[0:1], v20, v20, v31
	v_rcp_f32_e32 v34, v32
	v_div_fmas_f32 v26, v26, v33, v27
	v_div_fixup_f32 v21, v26, v21, v14
	v_fma_f32 v14, -v32, v34, 1.0
	v_fmac_f32_e32 v34, v14, v34
	v_div_scale_f32 v14, vcc, v31, v20, v31
	v_mul_f32_e32 v26, v14, v34
	v_fma_f32 v27, -v32, v26, v14
	v_fmac_f32_e32 v26, v27, v34
	v_fma_f32 v14, -v32, v26, v14
	v_lshlrev_b32_e32 v32, 16, v89
	v_and_b32_e32 v27, 0xffff0000, v89
	v_div_fmas_f32 v26, v14, v34, v26
	v_mul_f32_e32 v14, 0xbfb8aa3b, v32
	v_mul_f32_e32 v15, 0xbfb8aa3b, v27
	v_exp_f32_e32 v14, v14
	v_exp_f32_e32 v15, v15
	v_div_fixup_f32 v20, v26, v20, v31
	v_pk_mul_f32 v[20:21], v[24:25], v[20:21]
	v_lshlrev_b32_e32 v24, 16, v11
	v_pk_add_f32 v[14:15], v[14:15], 1.0 op_sel_hi:[1,0]
	v_and_b32_e32 v25, 0xffff0000, v11
	v_div_scale_f32 v26, s[0:1], v15, v15, v27
	v_rcp_f32_e32 v31, v26
	v_pk_mul_f32 v[24:25], v[10:11], v[24:25] op_sel_hi:[0,1]
	v_pk_mul_f32 v[24:25], v[8:9], v[24:25]
	v_fma_f32 v11, -v26, v31, 1.0
	v_fmac_f32_e32 v31, v11, v31
	v_div_scale_f32 v11, vcc, v27, v15, v27
	v_mul_f32_e32 v33, v11, v31
	v_fma_f32 v34, -v26, v33, v11
	v_fmac_f32_e32 v33, v34, v31
	v_fma_f32 v11, -v26, v33, v11
	v_div_scale_f32 v26, s[0:1], v14, v14, v32
	v_rcp_f32_e32 v34, v26
	v_div_fmas_f32 v11, v11, v31, v33
	v_div_fixup_f32 v15, v11, v15, v27
	v_fma_f32 v11, -v26, v34, 1.0
	v_fmac_f32_e32 v34, v11, v34
	v_div_scale_f32 v11, vcc, v32, v14, v32
	v_mul_f32_e32 v27, v11, v34
	v_fma_f32 v31, -v26, v27, v11
	v_fmac_f32_e32 v27, v31, v34
	v_fma_f32 v11, -v26, v27, v11
	v_lshlrev_b32_e32 v31, 16, v90
	v_and_b32_e32 v16, 0xffff0000, v90
	v_div_fmas_f32 v11, v11, v34, v27
	v_mul_f32_e32 v26, 0xbfb8aa3b, v31
	v_mul_f32_e32 v27, 0xbfb8aa3b, v16
	v_exp_f32_e32 v26, v26
	v_exp_f32_e32 v27, v27
	v_div_fixup_f32 v14, v11, v14, v32
	v_pk_mul_f32 v[14:15], v[24:25], v[14:15]
	v_lshlrev_b32_e32 v24, 16, v12
	v_pk_add_f32 v[26:27], v[26:27], 1.0 op_sel_hi:[1,0]
	v_and_b32_e32 v25, 0xffff0000, v12
	v_div_scale_f32 v11, s[0:1], v27, v27, v16
	v_rcp_f32_e32 v32, v11
	v_pk_mul_f32 v[24:25], v[10:11], v[24:25] op_sel_hi:[0,1]
	v_pk_mul_f32 v[24:25], v[2:3], v[24:25]
	v_fma_f32 v12, -v11, v32, 1.0
	v_fmac_f32_e32 v32, v12, v32
	v_div_scale_f32 v12, vcc, v16, v27, v16
	v_mul_f32_e32 v33, v12, v32
	v_fma_f32 v34, -v11, v33, v12
	v_fmac_f32_e32 v33, v34, v32
	v_fma_f32 v11, -v11, v33, v12
	v_div_scale_f32 v12, s[0:1], v26, v26, v31
	v_rcp_f32_e32 v34, v12
	v_div_fmas_f32 v11, v11, v32, v33
	v_div_fixup_f32 v27, v11, v27, v16
	v_and_b32_e32 v33, 0xffff0000, v91
	v_fma_f32 v11, -v12, v34, 1.0
	v_fmac_f32_e32 v34, v11, v34
	v_div_scale_f32 v11, vcc, v31, v26, v31
	v_mul_f32_e32 v16, v11, v34
	v_fma_f32 v32, -v12, v16, v11
	v_fmac_f32_e32 v16, v32, v34
	v_lshlrev_b32_e32 v32, 16, v91
	v_fma_f32 v11, -v12, v16, v11
	v_mul_f32_e32 v12, 0xbfb8aa3b, v32
	v_div_fmas_f32 v11, v11, v34, v16
	v_exp_f32_e32 v16, v12
	v_mul_f32_e32 v12, 0xbfb8aa3b, v33
	v_exp_f32_e32 v17, v12
	v_div_fixup_f32 v26, v11, v26, v31
	v_pk_mul_f32 v[24:25], v[24:25], v[26:27]
	v_lshlrev_b32_e32 v12, 16, v13
	v_pk_add_f32 v[16:17], v[16:17], 1.0 op_sel_hi:[1,0]
	v_and_b32_e32 v13, 0xffff0000, v13
	v_div_scale_f32 v26, s[0:1], v17, v17, v33
	v_rcp_f32_e32 v27, v26
	v_pk_mul_f32 v[10:11], v[10:11], v[12:13] op_sel_hi:[0,1]
	v_pk_mul_f32 v[10:11], v[4:5], v[10:11]
	v_fma_f32 v12, -v26, v27, 1.0
	v_fmac_f32_e32 v27, v12, v27
	v_div_scale_f32 v12, vcc, v33, v17, v33
	v_mul_f32_e32 v13, v12, v27
	v_fma_f32 v31, -v26, v13, v12
	v_fmac_f32_e32 v13, v31, v27
	v_fma_f32 v12, -v26, v13, v12
	v_div_scale_f32 v26, s[0:1], v16, v16, v32
	v_rcp_f32_e32 v31, v26
	v_div_fmas_f32 v12, v12, v27, v13
	v_div_fixup_f32 v13, v12, v17, v33
	v_fma_f32 v12, -v26, v31, 1.0
	v_fmac_f32_e32 v31, v12, v31
	v_div_scale_f32 v12, vcc, v32, v16, v32
	v_mul_f32_e32 v17, v12, v31
	v_fma_f32 v27, -v26, v17, v12
	v_fmac_f32_e32 v17, v27, v31
	v_fma_f32 v12, -v26, v17, v12
	v_div_fmas_f32 v12, v12, v31, v17
	v_div_fixup_f32 v12, v12, v16, v32
	v_pk_mul_f32 v[16:17], v[10:11], v[12:13]
	v_cvt_pk_bf16_f32 v10, v20, v21
	v_cvt_pk_bf16_f32 v11, v14, v15
	v_cvt_pk_bf16_f32 v12, v24, v25
	v_cvt_pk_bf16_f32 v13, v16, v17
	v_lshl_add_u64 v[14:15], s[36:37], 0, v[18:19]
	global_store_dwordx4 v[14:15], v[10:13], off sc1
	ds_read_b128 v[14:17], v29 offset:8448
	ds_read2_b32 v[34:35], v30 offset0:144 offset1:146
	v_or_b32_e32 v10, 16, v22
	v_mov_b32_e32 v11, v23
	v_lshlrev_b64 v[24:25], 11, v[10:11]
	v_or_b32_e32 v24, v24, v28
	v_lshl_add_u64 v[10:11], s[60:61], 0, v[24:25]
	v_lshlrev_b32_e32 v31, 16, v92
	v_and_b32_e32 v18, 0xffff0000, v92
	v_mul_f32_e32 v10, 0xbfb8aa3b, v31
	v_exp_f32_e32 v26, v10
	v_mul_f32_e32 v10, 0xbfb8aa3b, v18
	v_exp_f32_e32 v27, v10
	ds_read_b128 v[10:13], v29 offset:9504
	s_waitcnt lgkmcnt(2)
	v_lshlrev_b32_e32 v32, 16, v14
	v_and_b32_e32 v33, 0xffff0000, v14
	v_pk_add_f32 v[26:27], v[26:27], 1.0 op_sel_hi:[1,0]
	s_waitcnt lgkmcnt(1)
	v_pk_mul_f32 v[32:33], v[34:35], v[32:33] op_sel_hi:[0,1]
	v_div_scale_f32 v36, s[0:1], v27, v27, v18
	v_rcp_f32_e32 v37, v36
	v_pk_mul_f32 v[32:33], v[6:7], v[32:33]
	v_fma_f32 v14, -v36, v37, 1.0
	v_fmac_f32_e32 v37, v14, v37
	v_div_scale_f32 v14, vcc, v18, v27, v18
	v_mul_f32_e32 v38, v14, v37
	v_fma_f32 v39, -v36, v38, v14
	v_fmac_f32_e32 v38, v39, v37
	v_fma_f32 v14, -v36, v38, v14
	v_div_scale_f32 v36, s[0:1], v26, v26, v31
	v_rcp_f32_e32 v39, v36
	v_div_fmas_f32 v14, v14, v37, v38
	v_div_fixup_f32 v27, v14, v27, v18
	v_fma_f32 v14, -v36, v39, 1.0
	v_fmac_f32_e32 v39, v14, v39
	v_div_scale_f32 v14, vcc, v31, v26, v31
	v_mul_f32_e32 v18, v14, v39
	v_fma_f32 v37, -v36, v18, v14
	v_fmac_f32_e32 v18, v37, v39
	v_fma_f32 v14, -v36, v18, v14
	v_lshlrev_b32_e32 v36, 16, v93
	v_and_b32_e32 v37, 0xffff0000, v93
	v_div_fmas_f32 v14, v14, v39, v18
	v_mul_f32_e32 v18, 0xbfb8aa3b, v36
	v_mul_f32_e32 v19, 0xbfb8aa3b, v37
	v_exp_f32_e32 v18, v18
	v_exp_f32_e32 v19, v19
	v_div_fixup_f32 v26, v14, v26, v31
	v_pk_mul_f32 v[26:27], v[32:33], v[26:27]
	v_lshlrev_b32_e32 v14, 16, v15
	v_pk_add_f32 v[18:19], v[18:19], 1.0 op_sel_hi:[1,0]
	v_and_b32_e32 v15, 0xffff0000, v15
	v_div_scale_f32 v31, s[0:1], v19, v19, v37
	v_rcp_f32_e32 v32, v31
	v_pk_mul_f32 v[14:15], v[34:35], v[14:15] op_sel_hi:[0,1]
	v_pk_mul_f32 v[14:15], v[8:9], v[14:15]
	v_fma_f32 v33, -v31, v32, 1.0
	v_fmac_f32_e32 v32, v33, v32
	v_div_scale_f32 v33, vcc, v37, v19, v37
	v_mul_f32_e32 v38, v33, v32
	v_fma_f32 v39, -v31, v38, v33
	v_fmac_f32_e32 v38, v39, v32
	v_fma_f32 v31, -v31, v38, v33
	v_div_scale_f32 v33, s[0:1], v18, v18, v36
	v_rcp_f32_e32 v39, v33
	v_div_fmas_f32 v31, v31, v32, v38
	v_div_fixup_f32 v19, v31, v19, v37
	v_fma_f32 v31, -v33, v39, 1.0
	v_fmac_f32_e32 v39, v31, v39
	v_div_scale_f32 v31, vcc, v36, v18, v36
	v_mul_f32_e32 v32, v31, v39
	v_fma_f32 v37, -v33, v32, v31
	v_fmac_f32_e32 v32, v37, v39
	v_fma_f32 v31, -v33, v32, v31
	v_lshlrev_b32_e32 v37, 16, v94
	v_and_b32_e32 v20, 0xffff0000, v94
	v_div_fmas_f32 v31, v31, v39, v32
	v_mul_f32_e32 v32, 0xbfb8aa3b, v37
	v_mul_f32_e32 v33, 0xbfb8aa3b, v20
	v_exp_f32_e32 v32, v32
	v_exp_f32_e32 v33, v33
	v_div_fixup_f32 v18, v31, v18, v36
	v_pk_mul_f32 v[18:19], v[14:15], v[18:19]
	v_lshlrev_b32_e32 v14, 16, v16
	v_pk_add_f32 v[32:33], v[32:33], 1.0 op_sel_hi:[1,0]
	v_and_b32_e32 v15, 0xffff0000, v16
	v_div_scale_f32 v31, s[0:1], v33, v33, v20
	v_rcp_f32_e32 v36, v31
	v_pk_mul_f32 v[14:15], v[34:35], v[14:15] op_sel_hi:[0,1]
	v_pk_mul_f32 v[14:15], v[2:3], v[14:15]
	v_fma_f32 v16, -v31, v36, 1.0
	v_fmac_f32_e32 v36, v16, v36
	v_div_scale_f32 v16, vcc, v20, v33, v20
	v_mul_f32_e32 v38, v16, v36
	v_fma_f32 v39, -v31, v38, v16
	v_fmac_f32_e32 v38, v39, v36
	v_fma_f32 v16, -v31, v38, v16
	v_div_scale_f32 v31, s[0:1], v32, v32, v37
	v_rcp_f32_e32 v39, v31
	v_div_fmas_f32 v16, v16, v36, v38
	v_div_fixup_f32 v33, v16, v33, v20
	v_fma_f32 v16, -v31, v39, 1.0
	v_fmac_f32_e32 v39, v16, v39
	v_div_scale_f32 v16, vcc, v37, v32, v37
	v_mul_f32_e32 v20, v16, v39
	v_fma_f32 v36, -v31, v20, v16
	v_fmac_f32_e32 v20, v36, v39
	v_fma_f32 v16, -v31, v20, v16
	v_lshlrev_b32_e32 v31, 16, v95
	v_and_b32_e32 v36, 0xffff0000, v95
	v_div_fmas_f32 v16, v16, v39, v20
	v_mul_f32_e32 v20, 0xbfb8aa3b, v31
	v_mul_f32_e32 v21, 0xbfb8aa3b, v36
	v_exp_f32_e32 v20, v20
	v_exp_f32_e32 v21, v21
	v_div_fixup_f32 v32, v16, v32, v37
	v_pk_mul_f32 v[32:33], v[14:15], v[32:33]
	v_lshlrev_b32_e32 v14, 16, v17
	v_pk_add_f32 v[20:21], v[20:21], 1.0 op_sel_hi:[1,0]
	v_and_b32_e32 v15, 0xffff0000, v17
	v_div_scale_f32 v16, s[0:1], v21, v21, v36
	v_rcp_f32_e32 v37, v16
	v_pk_mul_f32 v[14:15], v[34:35], v[14:15] op_sel_hi:[0,1]
	v_pk_mul_f32 v[14:15], v[4:5], v[14:15]
	v_fma_f32 v17, -v16, v37, 1.0
	v_fmac_f32_e32 v37, v17, v37
	v_div_scale_f32 v17, vcc, v36, v21, v36
	v_mul_f32_e32 v34, v17, v37
	v_fma_f32 v38, -v16, v34, v17
	v_fmac_f32_e32 v34, v38, v37
	v_div_scale_f32 v38, s[0:1], v20, v20, v31
	v_rcp_f32_e32 v39, v38
	v_fma_f32 v16, -v16, v34, v17
	v_div_fmas_f32 v16, v16, v37, v34
	v_div_fixup_f32 v17, v16, v21, v36
	v_fma_f32 v16, -v38, v39, 1.0
	v_fmac_f32_e32 v39, v16, v39
	v_div_scale_f32 v16, vcc, v31, v20, v31
	v_mul_f32_e32 v21, v16, v39
	v_fma_f32 v34, -v38, v21, v16
	v_fmac_f32_e32 v21, v34, v39
	v_fma_f32 v16, -v38, v21, v16
	v_div_fmas_f32 v16, v16, v39, v21
	v_div_fixup_f32 v16, v16, v20, v31
	v_pk_mul_f32 v[20:21], v[14:15], v[16:17]
	v_cvt_pk_bf16_f32 v14, v26, v27
	v_cvt_pk_bf16_f32 v15, v18, v19
	v_cvt_pk_bf16_f32 v16, v32, v33
	v_cvt_pk_bf16_f32 v17, v20, v21
	v_lshl_add_u64 v[18:19], s[36:37], 0, v[24:25]
	global_store_dwordx4 v[18:19], v[14:17], off sc1
	s_waitcnt lgkmcnt(0)
	v_lshlrev_b32_e32 v24, 16, v10
	v_and_b32_e32 v25, 0xffff0000, v10
	v_or_b32_e32 v14, 18, v22
	v_mov_b32_e32 v15, v23
	v_lshlrev_b64 v[18:19], 11, v[14:15]
	v_or_b32_e32 v18, v18, v28
	v_lshl_add_u64 v[14:15], s[60:61], 0, v[18:19]
	v_mov_b32_e32 v10, v35
	v_pk_mul_f32 v[24:25], v[10:11], v[24:25] op_sel_hi:[0,1]
	v_pk_mul_f32 v[24:25], v[6:7], v[24:25]
	v_lshlrev_b32_e32 v26, 16, v96
	v_and_b32_e32 v14, 0xffff0000, v96
	v_mul_f32_e32 v20, 0xbfb8aa3b, v26
	v_mul_f32_e32 v21, 0xbfb8aa3b, v14
	v_exp_f32_e32 v20, v20
	v_exp_f32_e32 v21, v21
	s_nop 0
	v_pk_add_f32 v[20:21], v[20:21], 1.0 op_sel_hi:[1,0]
	s_nop 0
	v_div_scale_f32 v27, s[0:1], v21, v21, v14
	v_rcp_f32_e32 v31, v27
	s_nop 0
	v_fma_f32 v32, -v27, v31, 1.0
	v_fmac_f32_e32 v31, v32, v31
	v_div_scale_f32 v32, vcc, v14, v21, v14
	v_mul_f32_e32 v33, v32, v31
	v_fma_f32 v34, -v27, v33, v32
	v_fmac_f32_e32 v33, v34, v31
	v_fma_f32 v27, -v27, v33, v32
	v_div_scale_f32 v32, s[0:1], v20, v20, v26
	v_rcp_f32_e32 v34, v32
	v_div_fmas_f32 v27, v27, v31, v33
	v_div_fixup_f32 v21, v27, v21, v14
	v_fma_f32 v14, -v32, v34, 1.0
	v_fmac_f32_e32 v34, v14, v34
	v_div_scale_f32 v14, vcc, v26, v20, v26
	v_mul_f32_e32 v27, v14, v34
	v_fma_f32 v31, -v32, v27, v14
	v_fmac_f32_e32 v27, v31, v34
	v_fma_f32 v14, -v32, v27, v14
	v_lshlrev_b32_e32 v31, 16, v97
	v_and_b32_e32 v32, 0xffff0000, v97
	v_div_fmas_f32 v27, v14, v34, v27
	v_mul_f32_e32 v14, 0xbfb8aa3b, v31
	v_mul_f32_e32 v15, 0xbfb8aa3b, v32
	v_exp_f32_e32 v14, v14
	v_exp_f32_e32 v15, v15
	v_div_fixup_f32 v20, v27, v20, v26
	v_pk_mul_f32 v[20:21], v[24:25], v[20:21]
	v_lshlrev_b32_e32 v24, 16, v11
	v_pk_add_f32 v[14:15], v[14:15], 1.0 op_sel_hi:[1,0]
	v_and_b32_e32 v25, 0xffff0000, v11
	v_div_scale_f32 v26, s[0:1], v15, v15, v32
	v_rcp_f32_e32 v27, v26
	v_pk_mul_f32 v[24:25], v[10:11], v[24:25] op_sel_hi:[0,1]
	v_pk_mul_f32 v[24:25], v[8:9], v[24:25]
	v_fma_f32 v11, -v26, v27, 1.0
	v_fmac_f32_e32 v27, v11, v27
	v_div_scale_f32 v11, vcc, v32, v15, v32
	v_mul_f32_e32 v33, v11, v27
	v_fma_f32 v34, -v26, v33, v11
	v_fmac_f32_e32 v33, v34, v27
	v_fma_f32 v11, -v26, v33, v11
	v_div_scale_f32 v26, s[0:1], v14, v14, v31
	v_rcp_f32_e32 v34, v26
	v_div_fmas_f32 v11, v11, v27, v33
	v_div_fixup_f32 v15, v11, v15, v32
	v_fma_f32 v11, -v26, v34, 1.0
	v_fmac_f32_e32 v34, v11, v34
	v_div_scale_f32 v11, vcc, v31, v14, v31
	v_mul_f32_e32 v27, v11, v34
	v_fma_f32 v32, -v26, v27, v11
	v_fmac_f32_e32 v27, v32, v34
	v_fma_f32 v11, -v26, v27, v11
	v_lshlrev_b32_e32 v32, 16, v98
	v_and_b32_e32 v16, 0xffff0000, v98
	v_div_fmas_f32 v11, v11, v34, v27
	v_mul_f32_e32 v26, 0xbfb8aa3b, v32
	v_mul_f32_e32 v27, 0xbfb8aa3b, v16
	v_exp_f32_e32 v26, v26
	v_exp_f32_e32 v27, v27
	v_div_fixup_f32 v14, v11, v14, v31
	v_pk_mul_f32 v[14:15], v[24:25], v[14:15]
	v_lshlrev_b32_e32 v24, 16, v12
	v_pk_add_f32 v[26:27], v[26:27], 1.0 op_sel_hi:[1,0]
	v_and_b32_e32 v25, 0xffff0000, v12
	v_div_scale_f32 v11, s[0:1], v27, v27, v16
	v_rcp_f32_e32 v31, v11
	v_pk_mul_f32 v[24:25], v[10:11], v[24:25] op_sel_hi:[0,1]
	v_pk_mul_f32 v[24:25], v[2:3], v[24:25]
	v_fma_f32 v12, -v11, v31, 1.0
	v_fmac_f32_e32 v31, v12, v31
	v_div_scale_f32 v12, vcc, v16, v27, v16
	v_mul_f32_e32 v33, v12, v31
	v_fma_f32 v34, -v11, v33, v12
	v_fmac_f32_e32 v33, v34, v31
	v_fma_f32 v11, -v11, v33, v12
	v_div_scale_f32 v12, s[0:1], v26, v26, v32
	v_rcp_f32_e32 v34, v12
	v_div_fmas_f32 v11, v11, v31, v33
	v_div_fixup_f32 v27, v11, v27, v16
	v_and_b32_e32 v33, 0xffff0000, v99
	v_fma_f32 v11, -v12, v34, 1.0
	v_fmac_f32_e32 v34, v11, v34
	v_div_scale_f32 v11, vcc, v32, v26, v32
	v_mul_f32_e32 v16, v11, v34
	v_fma_f32 v31, -v12, v16, v11
	v_fmac_f32_e32 v16, v31, v34
	v_lshlrev_b32_e32 v31, 16, v99
	v_fma_f32 v11, -v12, v16, v11
	v_mul_f32_e32 v12, 0xbfb8aa3b, v31
	v_div_fmas_f32 v11, v11, v34, v16
	v_exp_f32_e32 v16, v12
	v_mul_f32_e32 v12, 0xbfb8aa3b, v33
	v_exp_f32_e32 v17, v12
	v_div_fixup_f32 v26, v11, v26, v32
	v_pk_mul_f32 v[24:25], v[24:25], v[26:27]
	v_lshlrev_b32_e32 v12, 16, v13
	v_pk_add_f32 v[16:17], v[16:17], 1.0 op_sel_hi:[1,0]
	v_and_b32_e32 v13, 0xffff0000, v13
	v_div_scale_f32 v26, s[0:1], v17, v17, v33
	v_rcp_f32_e32 v27, v26
	v_pk_mul_f32 v[10:11], v[10:11], v[12:13] op_sel_hi:[0,1]
	v_pk_mul_f32 v[10:11], v[4:5], v[10:11]
	v_fma_f32 v12, -v26, v27, 1.0
	v_fmac_f32_e32 v27, v12, v27
	v_div_scale_f32 v12, vcc, v33, v17, v33
	v_mul_f32_e32 v13, v12, v27
	v_fma_f32 v32, -v26, v13, v12
	v_fmac_f32_e32 v13, v32, v27
	v_fma_f32 v12, -v26, v13, v12
	v_div_scale_f32 v26, s[0:1], v16, v16, v31
	v_rcp_f32_e32 v32, v26
	v_div_fmas_f32 v12, v12, v27, v13
	v_div_fixup_f32 v13, v12, v17, v33
	v_fma_f32 v12, -v26, v32, 1.0
	v_fmac_f32_e32 v32, v12, v32
	v_div_scale_f32 v12, vcc, v31, v16, v31
	v_mul_f32_e32 v17, v12, v32
	v_fma_f32 v27, -v26, v17, v12
	v_fmac_f32_e32 v17, v27, v32
	v_fma_f32 v12, -v26, v17, v12
	v_div_fmas_f32 v12, v12, v32, v17
	v_div_fixup_f32 v12, v12, v16, v31
	v_pk_mul_f32 v[16:17], v[10:11], v[12:13]
	v_cvt_pk_bf16_f32 v10, v20, v21
	v_cvt_pk_bf16_f32 v11, v14, v15
	v_cvt_pk_bf16_f32 v12, v24, v25
	v_cvt_pk_bf16_f32 v13, v16, v17
	v_lshl_add_u64 v[14:15], s[36:37], 0, v[18:19]
	global_store_dwordx4 v[14:15], v[10:13], off sc1
	ds_read_b128 v[14:17], v29 offset:10560
	s_waitcnt lgkmcnt(0)
	v_lshlrev_b32_e32 v34, 16, v14
	v_or_b32_e32 v10, 20, v22
	v_mov_b32_e32 v11, v23
	v_lshlrev_b64 v[26:27], 11, v[10:11]
	v_or_b32_e32 v26, v26, v28
	v_lshl_add_u64 v[10:11], s[60:61], 0, v[26:27]
	v_and_b32_e32 v35, 0xffff0000, v14
	v_lshlrev_b32_e32 v31, 16, v100
	v_and_b32_e32 v18, 0xffff0000, v100
	v_mul_f32_e32 v10, 0xbfb8aa3b, v31
	v_exp_f32_e32 v32, v10
	v_mul_f32_e32 v10, 0xbfb8aa3b, v18
	v_exp_f32_e32 v33, v10
	ds_read2_b32 v[24:25], v30 offset0:148 offset1:150
	ds_read_b128 v[10:13], v29 offset:11616
	v_pk_add_f32 v[32:33], v[32:33], 1.0 op_sel_hi:[1,0]
	s_nop 0
	v_div_scale_f32 v36, s[0:1], v33, v33, v18
	v_rcp_f32_e32 v37, v36
	s_waitcnt lgkmcnt(1)
	v_pk_mul_f32 v[34:35], v[24:25], v[34:35] op_sel_hi:[0,1]
	v_pk_mul_f32 v[34:35], v[6:7], v[34:35]
	v_fma_f32 v14, -v36, v37, 1.0
	v_fmac_f32_e32 v37, v14, v37
	v_div_scale_f32 v14, vcc, v18, v33, v18
	v_mul_f32_e32 v38, v14, v37
	v_fma_f32 v39, -v36, v38, v14
	v_fmac_f32_e32 v38, v39, v37
	v_fma_f32 v14, -v36, v38, v14
	v_div_scale_f32 v36, s[0:1], v32, v32, v31
	v_rcp_f32_e32 v39, v36
	v_div_fmas_f32 v14, v14, v37, v38
	v_div_fixup_f32 v33, v14, v33, v18
	v_fma_f32 v14, -v36, v39, 1.0
	v_fmac_f32_e32 v39, v14, v39
	v_div_scale_f32 v14, vcc, v31, v32, v31
	v_mul_f32_e32 v18, v14, v39
	v_fma_f32 v37, -v36, v18, v14
	v_fmac_f32_e32 v18, v37, v39
	v_fma_f32 v14, -v36, v18, v14
	v_lshlrev_b32_e32 v36, 16, v101
	v_and_b32_e32 v37, 0xffff0000, v101
	v_div_fmas_f32 v14, v14, v39, v18
	v_mul_f32_e32 v18, 0xbfb8aa3b, v36
	v_mul_f32_e32 v19, 0xbfb8aa3b, v37
	v_exp_f32_e32 v18, v18
	v_exp_f32_e32 v19, v19
	v_div_fixup_f32 v32, v14, v32, v31
	v_pk_mul_f32 v[32:33], v[34:35], v[32:33]
	v_lshlrev_b32_e32 v14, 16, v15
	v_pk_add_f32 v[18:19], v[18:19], 1.0 op_sel_hi:[1,0]
	v_and_b32_e32 v15, 0xffff0000, v15
	v_div_scale_f32 v31, s[0:1], v19, v19, v37
	v_rcp_f32_e32 v34, v31
	v_pk_mul_f32 v[14:15], v[24:25], v[14:15] op_sel_hi:[0,1]
	v_pk_mul_f32 v[14:15], v[8:9], v[14:15]
	v_fma_f32 v35, -v31, v34, 1.0
	v_fmac_f32_e32 v34, v35, v34
	v_div_scale_f32 v35, vcc, v37, v19, v37
	v_mul_f32_e32 v38, v35, v34
	v_fma_f32 v39, -v31, v38, v35
	v_fmac_f32_e32 v38, v39, v34
	v_fma_f32 v31, -v31, v38, v35
	v_div_scale_f32 v35, s[0:1], v18, v18, v36
	v_rcp_f32_e32 v39, v35
	v_div_fmas_f32 v31, v31, v34, v38
	v_div_fixup_f32 v19, v31, v19, v37
	v_fma_f32 v31, -v35, v39, 1.0
	v_fmac_f32_e32 v39, v31, v39
	v_div_scale_f32 v31, vcc, v36, v18, v36
	v_mul_f32_e32 v34, v31, v39
	v_fma_f32 v37, -v35, v34, v31
	v_fmac_f32_e32 v34, v37, v39
	v_fma_f32 v31, -v35, v34, v31
	v_lshlrev_b32_e32 v37, 16, v102
	v_and_b32_e32 v20, 0xffff0000, v102
	v_div_fmas_f32 v31, v31, v39, v34
	v_mul_f32_e32 v34, 0xbfb8aa3b, v37
	v_mul_f32_e32 v35, 0xbfb8aa3b, v20
	v_exp_f32_e32 v34, v34
	v_exp_f32_e32 v35, v35
	v_div_fixup_f32 v18, v31, v18, v36
	v_pk_mul_f32 v[18:19], v[14:15], v[18:19]
	v_lshlrev_b32_e32 v14, 16, v16
	v_pk_add_f32 v[34:35], v[34:35], 1.0 op_sel_hi:[1,0]
	v_and_b32_e32 v15, 0xffff0000, v16
	v_div_scale_f32 v31, s[0:1], v35, v35, v20
	v_rcp_f32_e32 v36, v31
	v_pk_mul_f32 v[14:15], v[24:25], v[14:15] op_sel_hi:[0,1]
	v_pk_mul_f32 v[14:15], v[2:3], v[14:15]
	v_fma_f32 v16, -v31, v36, 1.0
	v_fmac_f32_e32 v36, v16, v36
	v_div_scale_f32 v16, vcc, v20, v35, v20
	v_mul_f32_e32 v38, v16, v36
	v_fma_f32 v39, -v31, v38, v16
	v_fmac_f32_e32 v38, v39, v36
	v_fma_f32 v16, -v31, v38, v16
	v_div_scale_f32 v31, s[0:1], v34, v34, v37
	v_rcp_f32_e32 v39, v31
	v_div_fmas_f32 v16, v16, v36, v38
	v_div_fixup_f32 v35, v16, v35, v20
	v_fma_f32 v16, -v31, v39, 1.0
	v_fmac_f32_e32 v39, v16, v39
	v_div_scale_f32 v16, vcc, v37, v34, v37
	v_mul_f32_e32 v20, v16, v39
	v_fma_f32 v36, -v31, v20, v16
	v_fmac_f32_e32 v20, v36, v39
	v_fma_f32 v16, -v31, v20, v16
	v_lshlrev_b32_e32 v31, 16, v103
	v_and_b32_e32 v36, 0xffff0000, v103
	v_div_fmas_f32 v16, v16, v39, v20
	v_mul_f32_e32 v20, 0xbfb8aa3b, v31
	v_mul_f32_e32 v21, 0xbfb8aa3b, v36
	v_exp_f32_e32 v20, v20
	v_exp_f32_e32 v21, v21
	v_div_fixup_f32 v34, v16, v34, v37
	v_pk_mul_f32 v[34:35], v[14:15], v[34:35]
	v_lshlrev_b32_e32 v14, 16, v17
	v_pk_add_f32 v[20:21], v[20:21], 1.0 op_sel_hi:[1,0]
	v_and_b32_e32 v15, 0xffff0000, v17
	v_div_scale_f32 v16, s[0:1], v21, v21, v36
	v_rcp_f32_e32 v37, v16
	v_pk_mul_f32 v[14:15], v[24:25], v[14:15] op_sel_hi:[0,1]
	v_pk_mul_f32 v[14:15], v[4:5], v[14:15]
	v_fma_f32 v17, -v16, v37, 1.0
	v_fmac_f32_e32 v37, v17, v37
	v_div_scale_f32 v17, vcc, v36, v21, v36
	v_mul_f32_e32 v24, v17, v37
	v_fma_f32 v38, -v16, v24, v17
	v_fmac_f32_e32 v24, v38, v37
	v_div_scale_f32 v38, s[0:1], v20, v20, v31
	v_rcp_f32_e32 v39, v38
	v_fma_f32 v16, -v16, v24, v17
	v_div_fmas_f32 v16, v16, v37, v24
	v_div_fixup_f32 v17, v16, v21, v36
	v_fma_f32 v16, -v38, v39, 1.0
	v_fmac_f32_e32 v39, v16, v39
	v_div_scale_f32 v16, vcc, v31, v20, v31
	v_mul_f32_e32 v21, v16, v39
	v_fma_f32 v24, -v38, v21, v16
	v_fmac_f32_e32 v21, v24, v39
	v_fma_f32 v16, -v38, v21, v16
	v_div_fmas_f32 v16, v16, v39, v21
	v_div_fixup_f32 v16, v16, v20, v31
	v_pk_mul_f32 v[20:21], v[14:15], v[16:17]
	v_cvt_pk_bf16_f32 v14, v32, v33
	v_cvt_pk_bf16_f32 v15, v18, v19
	v_cvt_pk_bf16_f32 v16, v34, v35
	v_cvt_pk_bf16_f32 v17, v20, v21
	v_lshl_add_u64 v[18:19], s[36:37], 0, v[26:27]
	global_store_dwordx4 v[18:19], v[14:17], off sc1
	s_waitcnt lgkmcnt(0)
	v_lshlrev_b32_e32 v26, 16, v10
	v_and_b32_e32 v27, 0xffff0000, v10
	v_or_b32_e32 v14, 22, v22
	v_mov_b32_e32 v15, v23
	v_lshlrev_b64 v[18:19], 11, v[14:15]
	v_or_b32_e32 v18, v18, v28
	v_lshl_add_u64 v[14:15], s[60:61], 0, v[18:19]
	v_mov_b32_e32 v10, v25
	v_pk_mul_f32 v[24:25], v[10:11], v[26:27] op_sel_hi:[0,1]
	v_pk_mul_f32 v[24:25], v[6:7], v[24:25]
	v_lshlrev_b32_e32 v31, 16, v104
	v_and_b32_e32 v14, 0xffff0000, v104
	v_mul_f32_e32 v20, 0xbfb8aa3b, v31
	v_mul_f32_e32 v21, 0xbfb8aa3b, v14
	v_exp_f32_e32 v20, v20
	v_exp_f32_e32 v21, v21
	s_nop 0
	v_pk_add_f32 v[20:21], v[20:21], 1.0 op_sel_hi:[1,0]
	s_nop 0
	v_div_scale_f32 v32, s[0:1], v21, v21, v14
	v_rcp_f32_e32 v33, v32
	s_nop 0
	v_fma_f32 v26, -v32, v33, 1.0
	v_fmac_f32_e32 v33, v26, v33
	v_div_scale_f32 v26, vcc, v14, v21, v14
	v_mul_f32_e32 v27, v26, v33
	v_fma_f32 v34, -v32, v27, v26
	v_fmac_f32_e32 v27, v34, v33
	v_fma_f32 v26, -v32, v27, v26
	v_div_scale_f32 v32, s[0:1], v20, v20, v31
	v_rcp_f32_e32 v34, v32
	v_div_fmas_f32 v26, v26, v33, v27
	v_div_fixup_f32 v21, v26, v21, v14
	v_fma_f32 v14, -v32, v34, 1.0
	v_fmac_f32_e32 v34, v14, v34
	v_div_scale_f32 v14, vcc, v31, v20, v31
	v_mul_f32_e32 v26, v14, v34
	v_fma_f32 v27, -v32, v26, v14
	v_fmac_f32_e32 v26, v27, v34
	v_fma_f32 v14, -v32, v26, v14
	v_lshlrev_b32_e32 v32, 16, v105
	v_and_b32_e32 v27, 0xffff0000, v105
	v_div_fmas_f32 v26, v14, v34, v26
	v_mul_f32_e32 v14, 0xbfb8aa3b, v32
	v_mul_f32_e32 v15, 0xbfb8aa3b, v27
	v_exp_f32_e32 v14, v14
	v_exp_f32_e32 v15, v15
	v_div_fixup_f32 v20, v26, v20, v31
	v_pk_mul_f32 v[20:21], v[24:25], v[20:21]
	v_lshlrev_b32_e32 v24, 16, v11
	v_pk_add_f32 v[14:15], v[14:15], 1.0 op_sel_hi:[1,0]
	v_and_b32_e32 v25, 0xffff0000, v11
	v_div_scale_f32 v26, s[0:1], v15, v15, v27
	v_rcp_f32_e32 v31, v26
	v_pk_mul_f32 v[24:25], v[10:11], v[24:25] op_sel_hi:[0,1]
	v_pk_mul_f32 v[24:25], v[8:9], v[24:25]
	v_fma_f32 v11, -v26, v31, 1.0
	v_fmac_f32_e32 v31, v11, v31
	v_div_scale_f32 v11, vcc, v27, v15, v27
	v_mul_f32_e32 v33, v11, v31
	v_fma_f32 v34, -v26, v33, v11
	v_fmac_f32_e32 v33, v34, v31
	v_fma_f32 v11, -v26, v33, v11
	v_div_scale_f32 v26, s[0:1], v14, v14, v32
	v_rcp_f32_e32 v34, v26
	v_div_fmas_f32 v11, v11, v31, v33
	v_div_fixup_f32 v15, v11, v15, v27
	v_fma_f32 v11, -v26, v34, 1.0
	v_fmac_f32_e32 v34, v11, v34
	v_div_scale_f32 v11, vcc, v32, v14, v32
	v_mul_f32_e32 v27, v11, v34
	v_fma_f32 v31, -v26, v27, v11
	v_fmac_f32_e32 v27, v31, v34
	v_fma_f32 v11, -v26, v27, v11
	v_lshlrev_b32_e32 v31, 16, v106
	v_and_b32_e32 v16, 0xffff0000, v106
	v_div_fmas_f32 v11, v11, v34, v27
	v_mul_f32_e32 v26, 0xbfb8aa3b, v31
	v_mul_f32_e32 v27, 0xbfb8aa3b, v16
	v_exp_f32_e32 v26, v26
	v_exp_f32_e32 v27, v27
	v_div_fixup_f32 v14, v11, v14, v32
	v_pk_mul_f32 v[14:15], v[24:25], v[14:15]
	v_lshlrev_b32_e32 v24, 16, v12
	v_pk_add_f32 v[26:27], v[26:27], 1.0 op_sel_hi:[1,0]
	v_and_b32_e32 v25, 0xffff0000, v12
	v_div_scale_f32 v11, s[0:1], v27, v27, v16
	v_rcp_f32_e32 v32, v11
	v_pk_mul_f32 v[24:25], v[10:11], v[24:25] op_sel_hi:[0,1]
	v_pk_mul_f32 v[24:25], v[2:3], v[24:25]
	v_fma_f32 v12, -v11, v32, 1.0
	v_fmac_f32_e32 v32, v12, v32
	v_div_scale_f32 v12, vcc, v16, v27, v16
	v_mul_f32_e32 v33, v12, v32
	v_fma_f32 v34, -v11, v33, v12
	v_fmac_f32_e32 v33, v34, v32
	v_fma_f32 v11, -v11, v33, v12
	v_div_scale_f32 v12, s[0:1], v26, v26, v31
	v_rcp_f32_e32 v34, v12
	v_div_fmas_f32 v11, v11, v32, v33
	v_div_fixup_f32 v27, v11, v27, v16
	v_and_b32_e32 v33, 0xffff0000, v107
	v_fma_f32 v11, -v12, v34, 1.0
	v_fmac_f32_e32 v34, v11, v34
	v_div_scale_f32 v11, vcc, v31, v26, v31
	v_mul_f32_e32 v16, v11, v34
	v_fma_f32 v32, -v12, v16, v11
	v_fmac_f32_e32 v16, v32, v34
	v_lshlrev_b32_e32 v32, 16, v107
	v_fma_f32 v11, -v12, v16, v11
	v_mul_f32_e32 v12, 0xbfb8aa3b, v32
	v_div_fmas_f32 v11, v11, v34, v16
	v_exp_f32_e32 v16, v12
	v_mul_f32_e32 v12, 0xbfb8aa3b, v33
	v_exp_f32_e32 v17, v12
	v_div_fixup_f32 v26, v11, v26, v31
	v_pk_mul_f32 v[24:25], v[24:25], v[26:27]
	v_lshlrev_b32_e32 v12, 16, v13
	v_pk_add_f32 v[16:17], v[16:17], 1.0 op_sel_hi:[1,0]
	v_and_b32_e32 v13, 0xffff0000, v13
	v_div_scale_f32 v26, s[0:1], v17, v17, v33
	v_rcp_f32_e32 v27, v26
	v_pk_mul_f32 v[10:11], v[10:11], v[12:13] op_sel_hi:[0,1]
	v_pk_mul_f32 v[10:11], v[4:5], v[10:11]
	v_fma_f32 v12, -v26, v27, 1.0
	v_fmac_f32_e32 v27, v12, v27
	v_div_scale_f32 v12, vcc, v33, v17, v33
	v_mul_f32_e32 v13, v12, v27
	v_fma_f32 v31, -v26, v13, v12
	v_fmac_f32_e32 v13, v31, v27
	v_fma_f32 v12, -v26, v13, v12
	v_div_scale_f32 v26, s[0:1], v16, v16, v32
	v_rcp_f32_e32 v31, v26
	v_div_fmas_f32 v12, v12, v27, v13
	v_div_fixup_f32 v13, v12, v17, v33
	v_fma_f32 v12, -v26, v31, 1.0
	v_fmac_f32_e32 v31, v12, v31
	v_div_scale_f32 v12, vcc, v32, v16, v32
	v_mul_f32_e32 v17, v12, v31
	v_fma_f32 v27, -v26, v17, v12
	v_fmac_f32_e32 v17, v27, v31
	v_fma_f32 v12, -v26, v17, v12
	v_div_fmas_f32 v12, v12, v31, v17
	v_div_fixup_f32 v12, v12, v16, v32
	v_pk_mul_f32 v[16:17], v[10:11], v[12:13]
	v_cvt_pk_bf16_f32 v10, v20, v21
	v_cvt_pk_bf16_f32 v11, v14, v15
	v_cvt_pk_bf16_f32 v12, v24, v25
	v_cvt_pk_bf16_f32 v13, v16, v17
	v_lshl_add_u64 v[14:15], s[36:37], 0, v[18:19]
	global_store_dwordx4 v[14:15], v[10:13], off sc1
	ds_read_b128 v[14:17], v29 offset:12672
	s_waitcnt lgkmcnt(0)
	v_lshlrev_b32_e32 v34, 16, v14
	v_or_b32_e32 v10, 24, v22
	v_mov_b32_e32 v11, v23
	v_lshlrev_b64 v[26:27], 11, v[10:11]
	v_or_b32_e32 v26, v26, v28
	v_lshl_add_u64 v[10:11], s[60:61], 0, v[26:27]
	v_and_b32_e32 v35, 0xffff0000, v14
	v_lshlrev_b32_e32 v31, 16, v108
	v_and_b32_e32 v18, 0xffff0000, v108
	v_mul_f32_e32 v10, 0xbfb8aa3b, v31
	v_exp_f32_e32 v32, v10
	v_mul_f32_e32 v10, 0xbfb8aa3b, v18
	v_exp_f32_e32 v33, v10
	ds_read2_b32 v[24:25], v30 offset0:152 offset1:154
	ds_read_b128 v[10:13], v29 offset:13728
	v_pk_add_f32 v[32:33], v[32:33], 1.0 op_sel_hi:[1,0]
	s_nop 0
	v_div_scale_f32 v36, s[0:1], v33, v33, v18
	v_rcp_f32_e32 v37, v36
	s_waitcnt lgkmcnt(1)
	v_pk_mul_f32 v[34:35], v[24:25], v[34:35] op_sel_hi:[0,1]
	v_pk_mul_f32 v[34:35], v[6:7], v[34:35]
	v_fma_f32 v14, -v36, v37, 1.0
	v_fmac_f32_e32 v37, v14, v37
	v_div_scale_f32 v14, vcc, v18, v33, v18
	v_mul_f32_e32 v38, v14, v37
	v_fma_f32 v39, -v36, v38, v14
	v_fmac_f32_e32 v38, v39, v37
	v_fma_f32 v14, -v36, v38, v14
	v_div_scale_f32 v36, s[0:1], v32, v32, v31
	v_rcp_f32_e32 v39, v36
	v_div_fmas_f32 v14, v14, v37, v38
	v_div_fixup_f32 v33, v14, v33, v18
	v_fma_f32 v14, -v36, v39, 1.0
	v_fmac_f32_e32 v39, v14, v39
	v_div_scale_f32 v14, vcc, v31, v32, v31
	v_mul_f32_e32 v18, v14, v39
	v_fma_f32 v37, -v36, v18, v14
	v_fmac_f32_e32 v18, v37, v39
	v_fma_f32 v14, -v36, v18, v14
	v_lshlrev_b32_e32 v36, 16, v109
	v_and_b32_e32 v37, 0xffff0000, v109
	v_div_fmas_f32 v14, v14, v39, v18
	v_mul_f32_e32 v18, 0xbfb8aa3b, v36
	v_mul_f32_e32 v19, 0xbfb8aa3b, v37
	v_exp_f32_e32 v18, v18
	v_exp_f32_e32 v19, v19
	v_div_fixup_f32 v32, v14, v32, v31
	v_pk_mul_f32 v[32:33], v[34:35], v[32:33]
	v_lshlrev_b32_e32 v14, 16, v15
	v_pk_add_f32 v[18:19], v[18:19], 1.0 op_sel_hi:[1,0]
	v_and_b32_e32 v15, 0xffff0000, v15
	v_div_scale_f32 v31, s[0:1], v19, v19, v37
	v_rcp_f32_e32 v34, v31
	v_pk_mul_f32 v[14:15], v[24:25], v[14:15] op_sel_hi:[0,1]
	v_pk_mul_f32 v[14:15], v[8:9], v[14:15]
	v_fma_f32 v35, -v31, v34, 1.0
	v_fmac_f32_e32 v34, v35, v34
	v_div_scale_f32 v35, vcc, v37, v19, v37
	v_mul_f32_e32 v38, v35, v34
	v_fma_f32 v39, -v31, v38, v35
	v_fmac_f32_e32 v38, v39, v34
	v_fma_f32 v31, -v31, v38, v35
	v_div_scale_f32 v35, s[0:1], v18, v18, v36
	v_rcp_f32_e32 v39, v35
	v_div_fmas_f32 v31, v31, v34, v38
	v_div_fixup_f32 v19, v31, v19, v37
	v_fma_f32 v31, -v35, v39, 1.0
	v_fmac_f32_e32 v39, v31, v39
	v_div_scale_f32 v31, vcc, v36, v18, v36
	v_mul_f32_e32 v34, v31, v39
	v_fma_f32 v37, -v35, v34, v31
	v_fmac_f32_e32 v34, v37, v39
	v_fma_f32 v31, -v35, v34, v31
	v_lshlrev_b32_e32 v37, 16, v110
	v_and_b32_e32 v20, 0xffff0000, v110
	v_div_fmas_f32 v31, v31, v39, v34
	v_mul_f32_e32 v34, 0xbfb8aa3b, v37
	v_mul_f32_e32 v35, 0xbfb8aa3b, v20
	v_exp_f32_e32 v34, v34
	v_exp_f32_e32 v35, v35
	v_div_fixup_f32 v18, v31, v18, v36
	v_pk_mul_f32 v[18:19], v[14:15], v[18:19]
	v_lshlrev_b32_e32 v14, 16, v16
	v_pk_add_f32 v[34:35], v[34:35], 1.0 op_sel_hi:[1,0]
	v_and_b32_e32 v15, 0xffff0000, v16
	v_div_scale_f32 v31, s[0:1], v35, v35, v20
	v_rcp_f32_e32 v36, v31
	v_pk_mul_f32 v[14:15], v[24:25], v[14:15] op_sel_hi:[0,1]
	v_pk_mul_f32 v[14:15], v[2:3], v[14:15]
	v_fma_f32 v16, -v31, v36, 1.0
	v_fmac_f32_e32 v36, v16, v36
	v_div_scale_f32 v16, vcc, v20, v35, v20
	v_mul_f32_e32 v38, v16, v36
	v_fma_f32 v39, -v31, v38, v16
	v_fmac_f32_e32 v38, v39, v36
	v_fma_f32 v16, -v31, v38, v16
	v_div_scale_f32 v31, s[0:1], v34, v34, v37
	v_rcp_f32_e32 v39, v31
	v_div_fmas_f32 v16, v16, v36, v38
	v_div_fixup_f32 v35, v16, v35, v20
	v_fma_f32 v16, -v31, v39, 1.0
	v_fmac_f32_e32 v39, v16, v39
	v_div_scale_f32 v16, vcc, v37, v34, v37
	v_mul_f32_e32 v20, v16, v39
	v_fma_f32 v36, -v31, v20, v16
	v_fmac_f32_e32 v20, v36, v39
	v_fma_f32 v16, -v31, v20, v16
	v_lshlrev_b32_e32 v31, 16, v111
	v_and_b32_e32 v36, 0xffff0000, v111
	v_div_fmas_f32 v16, v16, v39, v20
	v_mul_f32_e32 v20, 0xbfb8aa3b, v31
	v_mul_f32_e32 v21, 0xbfb8aa3b, v36
	v_exp_f32_e32 v20, v20
	v_exp_f32_e32 v21, v21
	v_div_fixup_f32 v34, v16, v34, v37
	v_pk_mul_f32 v[34:35], v[14:15], v[34:35]
	v_lshlrev_b32_e32 v14, 16, v17
	v_pk_add_f32 v[20:21], v[20:21], 1.0 op_sel_hi:[1,0]
	v_and_b32_e32 v15, 0xffff0000, v17
	v_div_scale_f32 v16, s[0:1], v21, v21, v36
	v_rcp_f32_e32 v37, v16
	v_pk_mul_f32 v[14:15], v[24:25], v[14:15] op_sel_hi:[0,1]
	v_pk_mul_f32 v[14:15], v[4:5], v[14:15]
	v_fma_f32 v17, -v16, v37, 1.0
	v_fmac_f32_e32 v37, v17, v37
	v_div_scale_f32 v17, vcc, v36, v21, v36
	v_mul_f32_e32 v24, v17, v37
	v_fma_f32 v38, -v16, v24, v17
	v_fmac_f32_e32 v24, v38, v37
	v_div_scale_f32 v38, s[0:1], v20, v20, v31
	v_rcp_f32_e32 v39, v38
	v_fma_f32 v16, -v16, v24, v17
	v_div_fmas_f32 v16, v16, v37, v24
	v_div_fixup_f32 v17, v16, v21, v36
	v_fma_f32 v16, -v38, v39, 1.0
	v_fmac_f32_e32 v39, v16, v39
	v_div_scale_f32 v16, vcc, v31, v20, v31
	v_mul_f32_e32 v21, v16, v39
	v_fma_f32 v24, -v38, v21, v16
	v_fmac_f32_e32 v21, v24, v39
	v_fma_f32 v16, -v38, v21, v16
	v_div_fmas_f32 v16, v16, v39, v21
	v_div_fixup_f32 v16, v16, v20, v31
	v_pk_mul_f32 v[20:21], v[14:15], v[16:17]
	v_cvt_pk_bf16_f32 v14, v32, v33
	v_cvt_pk_bf16_f32 v15, v18, v19
	v_cvt_pk_bf16_f32 v16, v34, v35
	v_cvt_pk_bf16_f32 v17, v20, v21
	v_lshl_add_u64 v[18:19], s[36:37], 0, v[26:27]
	global_store_dwordx4 v[18:19], v[14:17], off sc1
	s_waitcnt lgkmcnt(0)
	v_lshlrev_b32_e32 v26, 16, v10
	v_and_b32_e32 v27, 0xffff0000, v10
	v_or_b32_e32 v14, 26, v22
	v_mov_b32_e32 v15, v23
	v_lshlrev_b64 v[18:19], 11, v[14:15]
	v_or_b32_e32 v18, v18, v28
	v_lshl_add_u64 v[14:15], s[60:61], 0, v[18:19]
	v_mov_b32_e32 v10, v25
	v_pk_mul_f32 v[24:25], v[10:11], v[26:27] op_sel_hi:[0,1]
	v_pk_mul_f32 v[24:25], v[6:7], v[24:25]
	v_lshlrev_b32_e32 v31, 16, v112
	v_and_b32_e32 v14, 0xffff0000, v112
	v_mul_f32_e32 v20, 0xbfb8aa3b, v31
	v_mul_f32_e32 v21, 0xbfb8aa3b, v14
	v_exp_f32_e32 v20, v20
	v_exp_f32_e32 v21, v21
	s_nop 0
	v_pk_add_f32 v[20:21], v[20:21], 1.0 op_sel_hi:[1,0]
	s_nop 0
	v_div_scale_f32 v32, s[0:1], v21, v21, v14
	v_rcp_f32_e32 v33, v32
	s_nop 0
	v_fma_f32 v26, -v32, v33, 1.0
	v_fmac_f32_e32 v33, v26, v33
	v_div_scale_f32 v26, vcc, v14, v21, v14
	v_mul_f32_e32 v27, v26, v33
	v_fma_f32 v34, -v32, v27, v26
	v_fmac_f32_e32 v27, v34, v33
	v_fma_f32 v26, -v32, v27, v26
	v_div_scale_f32 v32, s[0:1], v20, v20, v31
	v_rcp_f32_e32 v34, v32
	v_div_fmas_f32 v26, v26, v33, v27
	v_div_fixup_f32 v21, v26, v21, v14
	v_fma_f32 v14, -v32, v34, 1.0
	v_fmac_f32_e32 v34, v14, v34
	v_div_scale_f32 v14, vcc, v31, v20, v31
	v_mul_f32_e32 v26, v14, v34
	v_fma_f32 v27, -v32, v26, v14
	v_fmac_f32_e32 v26, v27, v34
	v_fma_f32 v14, -v32, v26, v14
	v_lshlrev_b32_e32 v32, 16, v113
	v_and_b32_e32 v27, 0xffff0000, v113
	v_div_fmas_f32 v26, v14, v34, v26
	v_mul_f32_e32 v14, 0xbfb8aa3b, v32
	v_mul_f32_e32 v15, 0xbfb8aa3b, v27
	v_exp_f32_e32 v14, v14
	v_exp_f32_e32 v15, v15
	v_div_fixup_f32 v20, v26, v20, v31
	v_pk_mul_f32 v[20:21], v[24:25], v[20:21]
	v_lshlrev_b32_e32 v24, 16, v11
	v_pk_add_f32 v[14:15], v[14:15], 1.0 op_sel_hi:[1,0]
	v_and_b32_e32 v25, 0xffff0000, v11
	v_div_scale_f32 v26, s[0:1], v15, v15, v27
	v_rcp_f32_e32 v31, v26
	v_pk_mul_f32 v[24:25], v[10:11], v[24:25] op_sel_hi:[0,1]
	v_pk_mul_f32 v[24:25], v[8:9], v[24:25]
	v_fma_f32 v11, -v26, v31, 1.0
	v_fmac_f32_e32 v31, v11, v31
	v_div_scale_f32 v11, vcc, v27, v15, v27
	v_mul_f32_e32 v33, v11, v31
	v_fma_f32 v34, -v26, v33, v11
	v_fmac_f32_e32 v33, v34, v31
	v_fma_f32 v11, -v26, v33, v11
	v_div_scale_f32 v26, s[0:1], v14, v14, v32
	v_rcp_f32_e32 v34, v26
	v_div_fmas_f32 v11, v11, v31, v33
	v_div_fixup_f32 v15, v11, v15, v27
	v_fma_f32 v11, -v26, v34, 1.0
	v_fmac_f32_e32 v34, v11, v34
	v_div_scale_f32 v11, vcc, v32, v14, v32
	v_mul_f32_e32 v27, v11, v34
	v_fma_f32 v31, -v26, v27, v11
	v_fmac_f32_e32 v27, v31, v34
	v_fma_f32 v11, -v26, v27, v11
	v_lshlrev_b32_e32 v31, 16, v114
	v_and_b32_e32 v16, 0xffff0000, v114
	v_div_fmas_f32 v11, v11, v34, v27
	v_mul_f32_e32 v26, 0xbfb8aa3b, v31
	v_mul_f32_e32 v27, 0xbfb8aa3b, v16
	v_exp_f32_e32 v26, v26
	v_exp_f32_e32 v27, v27
	v_div_fixup_f32 v14, v11, v14, v32
	v_pk_mul_f32 v[14:15], v[24:25], v[14:15]
	v_lshlrev_b32_e32 v24, 16, v12
	v_pk_add_f32 v[26:27], v[26:27], 1.0 op_sel_hi:[1,0]
	v_and_b32_e32 v25, 0xffff0000, v12
	v_div_scale_f32 v11, s[0:1], v27, v27, v16
	v_rcp_f32_e32 v32, v11
	v_pk_mul_f32 v[24:25], v[10:11], v[24:25] op_sel_hi:[0,1]
	v_pk_mul_f32 v[24:25], v[2:3], v[24:25]
	v_fma_f32 v12, -v11, v32, 1.0
	v_fmac_f32_e32 v32, v12, v32
	v_div_scale_f32 v12, vcc, v16, v27, v16
	v_mul_f32_e32 v33, v12, v32
	v_fma_f32 v34, -v11, v33, v12
	v_fmac_f32_e32 v33, v34, v32
	v_fma_f32 v11, -v11, v33, v12
	v_div_scale_f32 v12, s[0:1], v26, v26, v31
	v_rcp_f32_e32 v34, v12
	v_div_fmas_f32 v11, v11, v32, v33
	v_div_fixup_f32 v27, v11, v27, v16
	v_and_b32_e32 v33, 0xffff0000, v115
	v_fma_f32 v11, -v12, v34, 1.0
	v_fmac_f32_e32 v34, v11, v34
	v_div_scale_f32 v11, vcc, v31, v26, v31
	v_mul_f32_e32 v16, v11, v34
	v_fma_f32 v32, -v12, v16, v11
	v_fmac_f32_e32 v16, v32, v34
	v_lshlrev_b32_e32 v32, 16, v115
	v_fma_f32 v11, -v12, v16, v11
	v_mul_f32_e32 v12, 0xbfb8aa3b, v32
	v_div_fmas_f32 v11, v11, v34, v16
	v_exp_f32_e32 v16, v12
	v_mul_f32_e32 v12, 0xbfb8aa3b, v33
	v_exp_f32_e32 v17, v12
	v_div_fixup_f32 v26, v11, v26, v31
	v_pk_mul_f32 v[24:25], v[24:25], v[26:27]
	v_lshlrev_b32_e32 v12, 16, v13
	v_pk_add_f32 v[16:17], v[16:17], 1.0 op_sel_hi:[1,0]
	v_and_b32_e32 v13, 0xffff0000, v13
	v_div_scale_f32 v26, s[0:1], v17, v17, v33
	v_rcp_f32_e32 v27, v26
	v_pk_mul_f32 v[10:11], v[10:11], v[12:13] op_sel_hi:[0,1]
	v_pk_mul_f32 v[10:11], v[4:5], v[10:11]
	v_fma_f32 v12, -v26, v27, 1.0
	v_fmac_f32_e32 v27, v12, v27
	v_div_scale_f32 v12, vcc, v33, v17, v33
	v_mul_f32_e32 v13, v12, v27
	v_fma_f32 v31, -v26, v13, v12
	v_fmac_f32_e32 v13, v31, v27
	v_fma_f32 v12, -v26, v13, v12
	v_div_scale_f32 v26, s[0:1], v16, v16, v32
	v_rcp_f32_e32 v31, v26
	v_div_fmas_f32 v12, v12, v27, v13
	v_div_fixup_f32 v13, v12, v17, v33
	v_fma_f32 v12, -v26, v31, 1.0
	v_fmac_f32_e32 v31, v12, v31
	v_div_scale_f32 v12, vcc, v32, v16, v32
	v_mul_f32_e32 v17, v12, v31
	v_fma_f32 v27, -v26, v17, v12
	v_fmac_f32_e32 v17, v27, v31
	v_fma_f32 v12, -v26, v17, v12
	v_div_fmas_f32 v12, v12, v31, v17
	v_div_fixup_f32 v12, v12, v16, v32
	v_pk_mul_f32 v[16:17], v[10:11], v[12:13]
	v_cvt_pk_bf16_f32 v10, v20, v21
	v_cvt_pk_bf16_f32 v11, v14, v15
	v_cvt_pk_bf16_f32 v12, v24, v25
	v_cvt_pk_bf16_f32 v13, v16, v17
	v_lshl_add_u64 v[14:15], s[36:37], 0, v[18:19]
	global_store_dwordx4 v[14:15], v[10:13], off sc1
	ds_read_b128 v[14:17], v29 offset:14784
	s_waitcnt lgkmcnt(0)
	v_and_b32_e32 v31, 0xffff0000, v14
	v_or_b32_e32 v10, 28, v22
	v_mov_b32_e32 v11, v23
	v_lshlrev_b64 v[26:27], 11, v[10:11]
	v_or_b32_e32 v26, v26, v28
	v_lshl_add_u64 v[10:11], s[60:61], 0, v[26:27]
	v_or_b32_e32 v22, 30, v22
	v_lshlrev_b32_e32 v34, 16, v116
	v_and_b32_e32 v18, 0xffff0000, v116
	v_mul_f32_e32 v10, 0xbfb8aa3b, v34
	v_exp_f32_e32 v32, v10
	v_mul_f32_e32 v10, 0xbfb8aa3b, v18
	v_exp_f32_e32 v33, v10
	ds_read2_b32 v[24:25], v30 offset0:156 offset1:158
	ds_read_b128 v[10:13], v29 offset:15840
	v_lshlrev_b32_e32 v30, 16, v14
	v_pk_add_f32 v[32:33], v[32:33], 1.0 op_sel_hi:[1,0]
	s_nop 0
	v_div_scale_f32 v29, s[0:1], v33, v33, v18
	v_rcp_f32_e32 v35, v29
	s_waitcnt lgkmcnt(1)
	v_pk_mul_f32 v[30:31], v[24:25], v[30:31] op_sel_hi:[0,1]
	v_pk_mul_f32 v[30:31], v[6:7], v[30:31]
	v_fma_f32 v14, -v29, v35, 1.0
	v_fmac_f32_e32 v35, v14, v35
	v_div_scale_f32 v14, vcc, v18, v33, v18
	v_mul_f32_e32 v36, v14, v35
	v_fma_f32 v37, -v29, v36, v14
	v_fmac_f32_e32 v36, v37, v35
	v_fma_f32 v14, -v29, v36, v14
	v_div_scale_f32 v29, s[0:1], v32, v32, v34
	v_rcp_f32_e32 v37, v29
	v_div_fmas_f32 v14, v14, v35, v36
	v_div_fixup_f32 v33, v14, v33, v18
	v_fma_f32 v14, -v29, v37, 1.0
	v_fmac_f32_e32 v37, v14, v37
	v_div_scale_f32 v14, vcc, v34, v32, v34
	v_mul_f32_e32 v18, v14, v37
	v_fma_f32 v35, -v29, v18, v14
	v_fmac_f32_e32 v18, v35, v37
	v_fma_f32 v14, -v29, v18, v14
	v_lshlrev_b32_e32 v29, 16, v117
	v_and_b32_e32 v35, 0xffff0000, v117
	v_div_fmas_f32 v14, v14, v37, v18
	v_mul_f32_e32 v18, 0xbfb8aa3b, v29
	v_mul_f32_e32 v19, 0xbfb8aa3b, v35
	v_exp_f32_e32 v18, v18
	v_exp_f32_e32 v19, v19
	v_div_fixup_f32 v32, v14, v32, v34
	v_pk_mul_f32 v[30:31], v[30:31], v[32:33]
	v_lshlrev_b32_e32 v14, 16, v15
	v_pk_add_f32 v[18:19], v[18:19], 1.0 op_sel_hi:[1,0]
	v_and_b32_e32 v15, 0xffff0000, v15
	v_div_scale_f32 v32, s[0:1], v19, v19, v35
	v_rcp_f32_e32 v33, v32
	v_pk_mul_f32 v[14:15], v[24:25], v[14:15] op_sel_hi:[0,1]
	v_pk_mul_f32 v[14:15], v[8:9], v[14:15]
	v_fma_f32 v34, -v32, v33, 1.0
	v_fmac_f32_e32 v33, v34, v33
	v_div_scale_f32 v34, vcc, v35, v19, v35
	v_mul_f32_e32 v36, v34, v33
	v_fma_f32 v37, -v32, v36, v34
	v_fmac_f32_e32 v36, v37, v33
	v_fma_f32 v32, -v32, v36, v34
	v_div_scale_f32 v34, s[0:1], v18, v18, v29
	v_rcp_f32_e32 v37, v34
	v_div_fmas_f32 v32, v32, v33, v36
	v_div_fixup_f32 v19, v32, v19, v35
	v_fma_f32 v32, -v34, v37, 1.0
	v_fmac_f32_e32 v37, v32, v37
	v_div_scale_f32 v32, vcc, v29, v18, v29
	v_mul_f32_e32 v33, v32, v37
	v_fma_f32 v35, -v34, v33, v32
	v_fmac_f32_e32 v33, v35, v37
	v_fma_f32 v32, -v34, v33, v32
	v_lshlrev_b32_e32 v35, 16, v118
	v_and_b32_e32 v20, 0xffff0000, v118
	v_div_fmas_f32 v34, v32, v37, v33
	v_mul_f32_e32 v32, 0xbfb8aa3b, v35
	v_mul_f32_e32 v33, 0xbfb8aa3b, v20
	v_exp_f32_e32 v32, v32
	v_exp_f32_e32 v33, v33
	v_div_fixup_f32 v18, v34, v18, v29
	v_pk_mul_f32 v[18:19], v[14:15], v[18:19]
	v_lshlrev_b32_e32 v14, 16, v16
	v_pk_add_f32 v[32:33], v[32:33], 1.0 op_sel_hi:[1,0]
	v_and_b32_e32 v15, 0xffff0000, v16
	v_div_scale_f32 v29, s[0:1], v33, v33, v20
	v_rcp_f32_e32 v34, v29
	v_pk_mul_f32 v[14:15], v[24:25], v[14:15] op_sel_hi:[0,1]
	v_pk_mul_f32 v[14:15], v[2:3], v[14:15]
	v_fma_f32 v16, -v29, v34, 1.0
	v_fmac_f32_e32 v34, v16, v34
	v_div_scale_f32 v16, vcc, v20, v33, v20
	v_mul_f32_e32 v36, v16, v34
	v_fma_f32 v37, -v29, v36, v16
	v_fmac_f32_e32 v36, v37, v34
	v_fma_f32 v16, -v29, v36, v16
	v_div_scale_f32 v29, s[0:1], v32, v32, v35
	v_rcp_f32_e32 v37, v29
	v_div_fmas_f32 v16, v16, v34, v36
	v_div_fixup_f32 v33, v16, v33, v20
	v_fma_f32 v16, -v29, v37, 1.0
	v_fmac_f32_e32 v37, v16, v37
	v_div_scale_f32 v16, vcc, v35, v32, v35
	v_mul_f32_e32 v20, v16, v37
	v_fma_f32 v34, -v29, v20, v16
	v_fmac_f32_e32 v20, v34, v37
	v_fma_f32 v16, -v29, v20, v16
	v_lshlrev_b32_e32 v29, 16, v119
	v_and_b32_e32 v34, 0xffff0000, v119
	v_div_fmas_f32 v16, v16, v37, v20
	v_mul_f32_e32 v20, 0xbfb8aa3b, v29
	v_mul_f32_e32 v21, 0xbfb8aa3b, v34
	v_exp_f32_e32 v20, v20
	v_exp_f32_e32 v21, v21
	v_div_fixup_f32 v32, v16, v32, v35
	v_pk_mul_f32 v[32:33], v[14:15], v[32:33]
	v_lshlrev_b32_e32 v14, 16, v17
	v_pk_add_f32 v[20:21], v[20:21], 1.0 op_sel_hi:[1,0]
	v_and_b32_e32 v15, 0xffff0000, v17
	v_div_scale_f32 v16, s[0:1], v21, v21, v34
	v_rcp_f32_e32 v35, v16
	v_pk_mul_f32 v[14:15], v[24:25], v[14:15] op_sel_hi:[0,1]
	v_pk_mul_f32 v[14:15], v[4:5], v[14:15]
	v_fma_f32 v17, -v16, v35, 1.0
	v_fmac_f32_e32 v35, v17, v35
	v_div_scale_f32 v17, vcc, v34, v21, v34
	v_mul_f32_e32 v24, v17, v35
	v_fma_f32 v36, -v16, v24, v17
	v_fmac_f32_e32 v24, v36, v35
	v_div_scale_f32 v36, s[0:1], v20, v20, v29
	v_rcp_f32_e32 v37, v36
	v_fma_f32 v16, -v16, v24, v17
	v_div_fmas_f32 v16, v16, v35, v24
	v_div_fixup_f32 v17, v16, v21, v34
	v_fma_f32 v16, -v36, v37, 1.0
	v_fmac_f32_e32 v37, v16, v37
	v_div_scale_f32 v16, vcc, v29, v20, v29
	v_mul_f32_e32 v21, v16, v37
	v_fma_f32 v24, -v36, v21, v16
	v_fmac_f32_e32 v21, v24, v37
	v_fma_f32 v16, -v36, v21, v16
	v_div_fmas_f32 v16, v16, v37, v21
	v_div_fixup_f32 v16, v16, v20, v29
	v_pk_mul_f32 v[20:21], v[14:15], v[16:17]
	v_cvt_pk_bf16_f32 v14, v30, v31
	v_cvt_pk_bf16_f32 v15, v18, v19
	v_cvt_pk_bf16_f32 v16, v32, v33
	v_cvt_pk_bf16_f32 v17, v20, v21
	v_lshl_add_u64 v[18:19], s[36:37], 0, v[26:27]
	global_store_dwordx4 v[18:19], v[14:17], off sc1
	v_lshlrev_b64 v[18:19], 11, v[22:23]
	v_or_b32_e32 v18, v18, v28
	v_lshl_add_u64 v[14:15], s[60:61], 0, v[18:19]
	s_waitcnt lgkmcnt(0)
	v_lshlrev_b32_e32 v22, 16, v10
	v_and_b32_e32 v23, 0xffff0000, v10
	v_mov_b32_e32 v10, v25
	v_pk_mul_f32 v[22:23], v[10:11], v[22:23] op_sel_hi:[0,1]
	v_pk_mul_f32 v[6:7], v[6:7], v[22:23]
	v_lshlrev_b32_e32 v24, 16, v120
	v_and_b32_e32 v14, 0xffff0000, v120
	v_mul_f32_e32 v20, 0xbfb8aa3b, v24
	v_mul_f32_e32 v21, 0xbfb8aa3b, v14
	v_exp_f32_e32 v20, v20
	v_exp_f32_e32 v21, v21
	s_nop 0
	v_pk_add_f32 v[20:21], v[20:21], 1.0 op_sel_hi:[1,0]
	s_nop 0
	v_div_scale_f32 v26, s[0:1], v21, v21, v14
	v_rcp_f32_e32 v27, v26
	s_nop 0
	v_fma_f32 v22, -v26, v27, 1.0
	v_fmac_f32_e32 v27, v22, v27
	v_div_scale_f32 v22, vcc, v14, v21, v14
	v_mul_f32_e32 v23, v22, v27
	v_fma_f32 v25, -v26, v23, v22
	v_fmac_f32_e32 v23, v25, v27
	v_div_scale_f32 v25, s[0:1], v20, v20, v24
	v_fma_f32 v22, -v26, v23, v22
	v_rcp_f32_e32 v26, v25
	v_div_fmas_f32 v22, v22, v27, v23
	v_div_fixup_f32 v21, v22, v21, v14
	v_fma_f32 v14, -v25, v26, 1.0
	v_fmac_f32_e32 v26, v14, v26
	v_div_scale_f32 v14, vcc, v24, v20, v24
	v_mul_f32_e32 v22, v14, v26
	v_fma_f32 v23, -v25, v22, v14
	v_fmac_f32_e32 v22, v23, v26
	v_fma_f32 v14, -v25, v22, v14
	v_lshlrev_b32_e32 v23, 16, v121
	v_and_b32_e32 v25, 0xffff0000, v121
	v_div_fmas_f32 v22, v14, v26, v22
	v_mul_f32_e32 v14, 0xbfb8aa3b, v23
	v_mul_f32_e32 v15, 0xbfb8aa3b, v25
	v_exp_f32_e32 v14, v14
	v_exp_f32_e32 v15, v15
	v_div_fixup_f32 v20, v22, v20, v24
	v_pk_mul_f32 v[6:7], v[6:7], v[20:21]
	v_lshlrev_b32_e32 v20, 16, v11
	v_pk_add_f32 v[14:15], v[14:15], 1.0 op_sel_hi:[1,0]
	v_and_b32_e32 v21, 0xffff0000, v11
	v_div_scale_f32 v22, s[0:1], v15, v15, v25
	v_rcp_f32_e32 v24, v22
	v_pk_mul_f32 v[20:21], v[10:11], v[20:21] op_sel_hi:[0,1]
	v_pk_mul_f32 v[8:9], v[8:9], v[20:21]
	v_fma_f32 v11, -v22, v24, 1.0
	v_fmac_f32_e32 v24, v11, v24
	v_div_scale_f32 v11, vcc, v25, v15, v25
	v_mul_f32_e32 v20, v11, v24
	v_fma_f32 v21, -v22, v20, v11
	v_fmac_f32_e32 v20, v21, v24
	v_div_scale_f32 v21, s[0:1], v14, v14, v23
	v_fma_f32 v11, -v22, v20, v11
	v_rcp_f32_e32 v22, v21
	v_div_fmas_f32 v11, v11, v24, v20
	v_div_fixup_f32 v15, v11, v15, v25
	v_fma_f32 v11, -v21, v22, 1.0
	v_fmac_f32_e32 v22, v11, v22
	v_div_scale_f32 v11, vcc, v23, v14, v23
	v_mul_f32_e32 v20, v11, v22
	v_fma_f32 v24, -v21, v20, v11
	v_fmac_f32_e32 v20, v24, v22
	v_fma_f32 v11, -v21, v20, v11
	v_div_fmas_f32 v11, v11, v22, v20
	v_lshlrev_b32_e32 v22, 16, v122
	v_and_b32_e32 v16, 0xffff0000, v122
	v_mul_f32_e32 v20, 0xbfb8aa3b, v22
	v_mul_f32_e32 v21, 0xbfb8aa3b, v16
	v_exp_f32_e32 v20, v20
	v_exp_f32_e32 v21, v21
	v_div_fixup_f32 v14, v11, v14, v23
	v_pk_mul_f32 v[8:9], v[8:9], v[14:15]
	v_lshlrev_b32_e32 v14, 16, v12
	v_pk_add_f32 v[20:21], v[20:21], 1.0 op_sel_hi:[1,0]
	v_and_b32_e32 v15, 0xffff0000, v12
	v_div_scale_f32 v11, s[0:1], v21, v21, v16
	v_rcp_f32_e32 v23, v11
	v_pk_mul_f32 v[14:15], v[10:11], v[14:15] op_sel_hi:[0,1]
	v_pk_mul_f32 v[2:3], v[2:3], v[14:15]
	v_fma_f32 v12, -v11, v23, 1.0
	v_fmac_f32_e32 v23, v12, v23
	v_div_scale_f32 v12, vcc, v16, v21, v16
	v_mul_f32_e32 v14, v12, v23
	v_fma_f32 v15, -v11, v14, v12
	v_fmac_f32_e32 v14, v15, v23
	v_fma_f32 v11, -v11, v14, v12
	v_div_scale_f32 v12, s[0:1], v20, v20, v22
	v_rcp_f32_e32 v24, v12
	v_div_fmas_f32 v11, v11, v23, v14
	v_div_fixup_f32 v15, v11, v21, v16
	v_and_b32_e32 v21, 0xffff0000, v123
	v_fma_f32 v11, -v12, v24, 1.0
	v_fmac_f32_e32 v24, v11, v24
	v_div_scale_f32 v11, vcc, v22, v20, v22
	v_mul_f32_e32 v14, v11, v24
	v_fma_f32 v16, -v12, v14, v11
	v_fmac_f32_e32 v14, v16, v24
	v_fma_f32 v11, -v12, v14, v11
	v_lshlrev_b32_e32 v12, 16, v123
	v_div_fmas_f32 v11, v11, v24, v14
	v_mul_f32_e32 v14, 0xbfb8aa3b, v12
	v_exp_f32_e32 v16, v14
	v_mul_f32_e32 v14, 0xbfb8aa3b, v21
	v_exp_f32_e32 v17, v14
	v_div_fixup_f32 v14, v11, v20, v22
	v_pk_mul_f32 v[14:15], v[2:3], v[14:15]
	v_lshlrev_b32_e32 v2, 16, v13
	v_pk_add_f32 v[16:17], v[16:17], 1.0 op_sel_hi:[1,0]
	v_and_b32_e32 v3, 0xffff0000, v13
	v_div_scale_f32 v11, s[0:1], v17, v17, v21
	v_rcp_f32_e32 v20, v11
	v_pk_mul_f32 v[2:3], v[10:11], v[2:3] op_sel_hi:[0,1]
	v_pk_mul_f32 v[2:3], v[4:5], v[2:3]
	v_fma_f32 v4, -v11, v20, 1.0
	v_fmac_f32_e32 v20, v4, v20
	v_div_scale_f32 v4, vcc, v21, v17, v21
	v_mul_f32_e32 v5, v4, v20
	v_fma_f32 v10, -v11, v5, v4
	v_fmac_f32_e32 v5, v10, v20
	v_div_scale_f32 v10, s[0:1], v16, v16, v12
	v_fma_f32 v4, -v11, v5, v4
	v_rcp_f32_e32 v11, v10
	v_div_fmas_f32 v4, v4, v20, v5
	v_div_fixup_f32 v5, v4, v17, v21
	v_fma_f32 v4, -v10, v11, 1.0
	v_fmac_f32_e32 v11, v4, v11
	v_div_scale_f32 v4, vcc, v12, v16, v12
	v_mul_f32_e32 v13, v4, v11
	v_fma_f32 v17, -v10, v13, v4
	v_fmac_f32_e32 v13, v17, v11
	v_fma_f32 v4, -v10, v13, v4
	v_div_fmas_f32 v4, v4, v11, v13
	v_div_fixup_f32 v4, v4, v16, v12
	v_pk_mul_f32 v[10:11], v[2:3], v[4:5]
	v_cvt_pk_bf16_f32 v2, v6, v7
	v_cvt_pk_bf16_f32 v3, v8, v9
	v_cvt_pk_bf16_f32 v4, v14, v15
	v_cvt_pk_bf16_f32 v5, v10, v11
	v_lshl_add_u64 v[6:7], s[36:37], 0, v[18:19]
	global_store_dwordx4 v[6:7], v[2:5], off sc1
	s_waitcnt vmcnt(0)
	s_barrier
	s_and_saveexec_b64 s[0:1], s[14:15]
	s_cbranch_execz .LBB0_1429
	s_add_i32 s6, 0, 0x22160
	v_mov_b32_e32 v2, s6
	s_waitcnt vmcnt(0) expcnt(0) lgkmcnt(0)
	ds_read_b32 v4, v2
	s_add_i32 s6, 0, 0x22164
	v_mov_b32_e32 v2, s6
	ds_read_b32 v2, v2
	s_waitcnt lgkmcnt(1)
	v_cmp_ne_u32_e32 vcc, 0, v4
	s_cbranch_vccnz .LBB0_1393
	v_readlane_b32 s8, v251, 53
	v_readlane_b32 s9, v251, 54
	s_load_dwordx2 s[6:7], s[8:9], 0x4
	s_mov_b32 s33, 1
	v_mov_b32_e32 v18, 0
	s_waitcnt lgkmcnt(0)
	s_mul_i32 s6, s6, s7
	s_lshl_b32 s60, s6, 8
	s_add_u32 s6, s34, 0x4200
	s_addc_u32 s7, s35, 0
	s_add_u32 s8, s34, 0x4400
	s_addc_u32 s9, s35, 0
	s_add_u32 s10, s34, 0x4500
	s_addc_u32 s11, s35, 0
	s_add_u32 s12, s34, 0x4600
	s_addc_u32 s13, s35, 0
	s_add_u32 s16, s34, 0x4700
	s_addc_u32 s17, s35, 0
	s_add_u32 s18, s34, 0x4800
	s_addc_u32 s19, s35, 0
	s_add_u32 s20, s34, 0x4900
	s_addc_u32 s21, s35, 0
	s_add_u32 s22, s34, 0x4a00
	s_addc_u32 s23, s35, 0
	s_add_u32 s24, s34, 0x4b00
	s_addc_u32 s25, s35, 0
	s_add_u32 s26, s34, 0x4c00
	s_addc_u32 s27, s35, 0
	s_add_u32 s28, s34, 0x4d00
	s_addc_u32 s29, s35, 0
	s_add_u32 s30, s34, 0x4e00
	s_addc_u32 s31, s35, 0
	s_add_u32 s38, s34, 0x4f00
	s_addc_u32 s39, s35, 0
	s_add_u32 s40, s34, 0x5000
	s_addc_u32 s41, s35, 0
	s_add_u32 s42, s34, 0x5100
	s_addc_u32 s43, s35, 0
	s_add_u32 s44, s34, 0x5200
	s_addc_u32 s45, s35, 0
	s_add_u32 s46, s34, 0x5300
	s_addc_u32 s47, s35, 0
	s_branch .LBB0_1381
